# nt (streaming) policy also on the gate phase's V / UZ tile loads (on top of rownorm/finalnorm row loads)
# speedup vs baseline: 1.0083x; 1.0083x over previous
.LBB0_190:
	s_ashr_i32 s12, s42, 4
	s_and_b32 s16, s42, 7
	s_and_b32 s17, s12, 0x7ffffff8
	s_or_b32 s16, s17, s16
	s_lshl_b32 s16, s16, 1
	s_bfe_u32 s17, s42, 0x10006
	s_or_b32 s16, s16, s17
	s_waitcnt lgkmcnt(0)
	s_barrier
	s_and_saveexec_b64 s[18:19], s[4:5]
	s_cbranch_execz .LBB0_192
	v_lshl_add_u32 v0, s16, 7, v153
	v_ashrrev_i32_e32 v1, 31, v0
	v_lshlrev_b64 v[0:1], 8, v[0:1]
	v_lshl_add_u64 v[60:61], s[10:11], 0, v[0:1]
	global_load_dwordx4 v[0:3], v[60:61], off nt
	global_load_dwordx4 v[4:7], v[60:61], off offset:16
	global_load_dwordx4 v[8:11], v[60:61], off offset:32
	global_load_dwordx4 v[12:15], v[60:61], off offset:48
	global_load_dwordx4 v[16:19], v[60:61], off offset:64
	global_load_dwordx4 v[20:23], v[60:61], off offset:80
	global_load_dwordx4 v[24:27], v[60:61], off offset:96
	global_load_dwordx4 v[28:31], v[60:61], off offset:112
	global_load_dwordx4 v[32:35], v[60:61], off offset:128
	global_load_dwordx4 v[36:39], v[60:61], off offset:144
	global_load_dwordx4 v[40:43], v[60:61], off offset:160
	global_load_dwordx4 v[44:47], v[60:61], off offset:176
	global_load_dwordx4 v[48:51], v[60:61], off offset:192
	global_load_dwordx4 v[52:55], v[60:61], off offset:208
	global_load_dwordx4 v[56:59], v[60:61], off offset:224
	s_nop 0
	global_load_dwordx4 v[60:63], v[60:61], off offset:240
	s_waitcnt vmcnt(15)
	v_pk_add_f32 v[0:1], v[0:1], 0 op_sel_hi:[1,0]
	s_nop 0
	v_pk_add_f32 v[0:1], v[0:1], v[2:3]
	s_waitcnt vmcnt(14)
	v_pk_add_f32 v[0:1], v[0:1], v[4:5]
	s_nop 0
	v_pk_add_f32 v[0:1], v[0:1], v[6:7]
	s_waitcnt vmcnt(13)
	v_pk_add_f32 v[0:1], v[0:1], v[8:9]
	s_nop 0
	v_pk_add_f32 v[0:1], v[0:1], v[10:11]
	s_waitcnt vmcnt(12)
	v_pk_add_f32 v[0:1], v[0:1], v[12:13]
	s_nop 0
	v_pk_add_f32 v[0:1], v[0:1], v[14:15]
	s_waitcnt vmcnt(11)
	v_pk_add_f32 v[0:1], v[0:1], v[16:17]
	s_nop 0
	v_pk_add_f32 v[0:1], v[0:1], v[18:19]
	s_waitcnt vmcnt(10)
	v_pk_add_f32 v[0:1], v[0:1], v[20:21]
	s_nop 0
	v_pk_add_f32 v[0:1], v[0:1], v[22:23]
	s_waitcnt vmcnt(9)
	v_pk_add_f32 v[0:1], v[0:1], v[24:25]
	s_nop 0
	v_pk_add_f32 v[0:1], v[0:1], v[26:27]
	s_waitcnt vmcnt(8)
	v_pk_add_f32 v[0:1], v[0:1], v[28:29]
	s_nop 0
	v_pk_add_f32 v[0:1], v[0:1], v[30:31]
	s_waitcnt vmcnt(7)
	v_pk_add_f32 v[0:1], v[0:1], v[32:33]
	s_nop 0
	v_pk_add_f32 v[0:1], v[0:1], v[34:35]
	s_waitcnt vmcnt(6)
	v_pk_add_f32 v[0:1], v[0:1], v[36:37]
	s_nop 0
	v_pk_add_f32 v[0:1], v[0:1], v[38:39]
	s_waitcnt vmcnt(5)
	v_pk_add_f32 v[0:1], v[0:1], v[40:41]
	s_nop 0
	v_pk_add_f32 v[0:1], v[0:1], v[42:43]
	s_waitcnt vmcnt(4)
	v_pk_add_f32 v[0:1], v[0:1], v[44:45]
	s_nop 0
	v_pk_add_f32 v[0:1], v[0:1], v[46:47]
	s_waitcnt vmcnt(3)
	v_pk_add_f32 v[0:1], v[0:1], v[48:49]
	s_nop 0
	v_pk_add_f32 v[0:1], v[0:1], v[50:51]
	s_waitcnt vmcnt(2)
	v_pk_add_f32 v[0:1], v[0:1], v[52:53]
	s_nop 0
	v_pk_add_f32 v[0:1], v[0:1], v[54:55]
	s_waitcnt vmcnt(1)
	v_pk_add_f32 v[0:1], v[0:1], v[56:57]
	s_nop 0
	v_pk_add_f32 v[0:1], v[0:1], v[58:59]
	s_waitcnt vmcnt(0)
	v_pk_add_f32 v[0:1], v[0:1], v[60:61]
	s_nop 0
	v_pk_add_f32 v[0:1], v[0:1], v[62:63]
	s_nop 0
	v_pk_mul_f32 v[0:1], v[0:1], s[14:15] op_sel_hi:[1,0]
	s_nop 0
	v_fma_f32 v1, -v0, v0, v1
	v_max_f32_e32 v1, 0, v1
	v_add_f32_e32 v1, 0x358637bd, v1
	v_mul_f32_e32 v2, 0x4b800000, v1
	v_cmp_gt_f32_e32 vcc, s40, v1
	s_nop 1
	v_cndmask_b32_e32 v1, v1, v2, vcc
	v_rsq_f32_e32 v1, v1
	s_nop 0
	v_mul_f32_e32 v2, 0x45800000, v1
	v_cndmask_b32_e32 v1, v1, v2, vcc
	ds_write2st64_b32 v172, v0, v1 offset1:2

.LBB0_199:
	v_add_u32_e32 v0, s22, v153
	v_ashrrev_i32_e32 v8, 4, v0
	v_add_u32_e32 v0, 0x200, v0
	v_ashrrev_i32_e32 v10, 4, v0
	v_ashrrev_i32_e32 v9, 31, v8
	v_ashrrev_i32_e32 v11, 31, v10
	s_waitcnt lgkmcnt(1)
	v_lshl_add_u64 v[0:1], s[16:17], 0, v[8:9]
	s_waitcnt lgkmcnt(0)
	v_lshl_add_u64 v[2:3], s[16:17], 0, v[10:11]
	v_lshlrev_b64 v[0:1], 8, v[0:1]
	v_lshlrev_b64 v[2:3], 8, v[2:3]
	v_lshl_add_u64 v[0:1], v[150:151], 0, v[0:1]
	v_lshl_add_u64 v[4:5], v[150:151], 0, v[2:3]
	global_load_dwordx4 v[0:3], v[0:1], off nt
	s_nop 0
	global_load_dwordx4 v[4:7], v[4:5], off nt
	s_addk_i32 s22, 0x400
	s_cmpk_eq_i32 s22, 0x1000
	v_mad_u64_u32 v[8:9], s[48:49], v8, s15, v[152:153]
	v_mad_u64_u32 v[10:11], s[48:49], v10, s15, v[152:153]
	s_waitcnt vmcnt(1)
	ds_write_b128 v8, v[0:3] offset:18432
	s_waitcnt vmcnt(0)
	ds_write_b128 v10, v[4:7] offset:18432
	s_cbranch_scc0 .LBB0_199
	s_waitcnt lgkmcnt(0)
	s_barrier
	ds_read_b128 v[0:3], v154
	ds_read_b128 v[8:11], v155 offset:18432
	ds_read_b128 v[136:139], v154 offset:32
	ds_read_b128 v[12:15], v155 offset:18464
	ds_read_b128 v[4:7], v154 offset:4608
	ds_read_b128 v[132:135], v154 offset:4640
	s_waitcnt lgkmcnt(4)
	v_mfma_f32_32x32x16_bf16 v[48:63], v[0:3], v[8:11], 0
	s_and_b32 s16, s41, 7
	s_lshl_b32 s12, s12, 1
	s_lshl_b32 s16, s16, 1
	s_and_b32 s12, s12, 0x1fffff0
	s_and_b32 s17, s43, 1
	s_or_b32 s12, s12, s16
	s_or_b32 s12, s12, s17
	s_waitcnt lgkmcnt(1)
	v_mfma_f32_32x32x16_bf16 v[32:47], v[4:7], v[8:11], 0
	s_mov_b64 s[16:17], 0
	v_mfma_f32_32x32x16_bf16 v[48:63], v[136:139], v[12:15], v[48:63]
	s_waitcnt lgkmcnt(0)
	v_mfma_f32_32x32x16_bf16 v[32:47], v[132:135], v[12:15], v[32:47]
	ds_read_b128 v[128:131], v154 offset:64
	ds_read_b128 v[8:11], v155 offset:18496
	ds_read_b128 v[116:119], v154 offset:96
	ds_read_b128 v[12:15], v155 offset:18528
	ds_read_b128 v[124:127], v154 offset:4672
	ds_read_b128 v[112:115], v154 offset:4704
	s_waitcnt lgkmcnt(4)
	v_mfma_f32_32x32x16_bf16 v[48:63], v[128:131], v[8:11], v[48:63]
	s_waitcnt lgkmcnt(1)
	v_mfma_f32_32x32x16_bf16 v[32:47], v[124:127], v[8:11], v[32:47]
	v_mfma_f32_32x32x16_bf16 v[48:63], v[116:119], v[12:15], v[48:63]
	s_waitcnt lgkmcnt(0)
	v_mfma_f32_32x32x16_bf16 v[32:47], v[112:115], v[12:15], v[32:47]
	ds_read_b128 v[108:111], v154 offset:55296
	ds_read_b128 v[8:11], v180
	ds_read_b128 v[12:15], v180 offset:32
	ds_read_b128 v[92:95], v154 offset:55328
	ds_read_b128 v[100:103], v154 offset:59904
	ds_read_b128 v[88:91], v154 offset:59936
	ds_read_b128 v[84:87], v154 offset:55360
	s_waitcnt lgkmcnt(5)
	v_mfma_f32_32x32x16_bf16 v[48:63], v[108:111], v[8:11], v[48:63]
	s_waitcnt lgkmcnt(2)
	v_mfma_f32_32x32x16_bf16 v[32:47], v[100:103], v[8:11], v[32:47]
	v_mfma_f32_32x32x16_bf16 v[48:63], v[92:95], v[12:15], v[48:63]
	s_waitcnt lgkmcnt(1)
	v_mfma_f32_32x32x16_bf16 v[32:47], v[88:91], v[12:15], v[32:47]
	ds_read_b128 v[12:15], v180 offset:64
	ds_read_b128 v[72:75], v154 offset:59968
	ds_read_b128 v[80:83], v154 offset:55392
	ds_read_b128 v[16:19], v180 offset:96
	ds_read_b128 v[8:11], v155 offset:23040
	ds_read_b128 v[144:147], v155 offset:23072
	ds_read_b128 v[140:143], v155 offset:23104
	ds_read_b128 v[120:123], v155 offset:23136
	ds_read_b128 v[104:107], v180 offset:4608
	ds_read_b128 v[96:99], v180 offset:4640
	ds_read_b128 v[64:67], v154 offset:60000
	ds_read_b128 v[76:79], v180 offset:4672
	ds_read_b128 v[68:71], v180 offset:4704
	s_waitcnt lgkmcnt(0)
	s_barrier
	v_mfma_f32_32x32x16_bf16 v[48:63], v[84:87], v[12:15], v[48:63]
	v_mfma_f32_32x32x16_bf16 v[32:47], v[72:75], v[12:15], v[32:47]
	v_lshl_add_u32 v12, s12, 7, v178
	v_ashrrev_i32_e32 v13, 31, v12
	v_lshlrev_b64 v[12:13], 12, v[12:13]
	v_lshl_or_b32 v12, s18, 9, v12
	v_lshl_add_u64 v[168:169], v[166:167], 0, v[12:13]
	v_mov_b32_e32 v12, v192
	v_mfma_f32_32x32x16_bf16 v[48:63], v[80:83], v[16:19], v[48:63]
	v_mfma_f32_32x32x16_bf16 v[32:47], v[64:67], v[16:19], v[32:47]
.LBB0_201:
	v_lshl_add_u64 v[22:23], v[168:169], 0, s[16:17]
	v_add_co_u32_e32 v14, vcc, 0x6000000, v22
	s_add_u32 s16, s16, 0x20000
	s_nop 0
	v_addc_co_u32_e32 v15, vcc, 0, v23, vcc
	v_add_co_u32_e32 v18, vcc, 0x6008000, v22
	s_addc_u32 s17, s17, 0
	s_nop 0
	v_addc_co_u32_e32 v19, vcc, 0, v23, vcc
	v_add_co_u32_e32 v24, vcc, 0x6010000, v22
	global_load_dwordx4 v[14:17], v[14:15], off nt
	s_nop 0
	global_load_dwordx4 v[18:21], v[18:19], off nt
	v_addc_co_u32_e32 v25, vcc, 0, v23, vcc
	v_add_co_u32_e32 v26, vcc, 0x6018000, v22
	s_cmp_lg_u32 s16, 0x40000
	s_nop 0
	v_addc_co_u32_e32 v27, vcc, 0, v23, vcc
	global_load_dwordx4 v[22:25], v[24:25], off nt
	s_nop 0
	global_load_dwordx4 v[26:29], v[26:27], off nt
	s_waitcnt vmcnt(3)
	ds_write_b128 v12, v[14:17]
	s_waitcnt vmcnt(2)
	ds_write_b128 v12, v[18:21] offset:1152
	s_waitcnt vmcnt(1)
	ds_write_b128 v12, v[22:25] offset:2304
	s_waitcnt vmcnt(0)
	ds_write_b128 v12, v[26:29] offset:3456
	v_add_u32_e32 v12, 0x1200, v12
	s_cbranch_scc1 .LBB0_201
	v_mfma_f32_32x32x16_bf16 v[16:31], v[0:3], v[8:11], 0
	v_add_u32_e32 v170, s19, v179
	v_ashrrev_i32_e32 v171, 31, v170
	v_lshlrev_b64 v[194:195], 2, v[170:171]
	v_lshl_add_u64 v[170:171], s[46:47], 0, v[194:195]
	s_lshl_b32 s12, s18, 7
	s_waitcnt lgkmcnt(0)
	s_mov_b64 s[16:17], 0
	v_mfma_f32_32x32x16_bf16 v[0:15], v[4:7], v[8:11], 0
	v_mfma_f32_32x32x16_bf16 v[16:31], v[136:139], v[144:147], v[16:31]
	global_load_dword v138, v[170:171], off
	v_lshl_add_u64 v[136:137], s[44:45], 0, v[194:195]
	v_add_u32_e32 v194, s12, v156
	global_load_dword v139, v[136:137], off
	v_ashrrev_i32_e32 v195, 31, v194
	v_mfma_f32_32x32x16_bf16 v[0:15], v[132:135], v[144:147], v[0:15]
	v_lshl_add_u64 v[134:135], v[194:195], 2, s[50:51]
	v_lshl_add_u64 v[132:133], s[12:13], 0, v[156:157]
	v_lshl_add_u64 v[132:133], v[132:133], 2, s[50:51]
	global_load_dword v213, v[134:135], off
	global_load_dwordx3 v[210:212], v[132:133], off offset:4
	v_mfma_f32_32x32x16_bf16 v[16:31], v[128:131], v[140:143], v[16:31]
	global_load_dwordx4 v[128:131], v[132:133], off offset:32
	ds_read_b128 v[144:147], v182 offset:1536
	ds_read_b128 v[194:197], v182 offset:1024
	s_waitcnt lgkmcnt(1)
	v_sub_f32_e32 v48, v48, v144
	v_sub_f32_e32 v49, v49, v145
	v_mfma_f32_32x32x16_bf16 v[0:15], v[124:127], v[140:143], v[0:15]
	ds_read_u16 v214, v183
	ds_read_b128 v[124:127], v184 offset:1024
	ds_read_b128 v[140:143], v184 offset:1536
	ds_read_b128 v[198:201], v185 offset:1024
	global_load_dwordx4 v[202:205], v[132:133], off offset:64
	global_load_dwordx4 v[206:209], v[132:133], off offset:96
	s_waitcnt lgkmcnt(3)
	v_lshlrev_b32_e32 v144, 16, v214
	v_sub_f32_e32 v50, v50, v146
	v_sub_f32_e32 v51, v51, v147
	s_waitcnt lgkmcnt(1)
	v_sub_f32_e32 v52, v52, v140
	v_sub_f32_e32 v53, v53, v141
	v_mfma_f32_32x32x16_bf16 v[0:15], v[112:115], v[120:123], v[0:15]
	v_sub_f32_e32 v54, v54, v142
	v_sub_f32_e32 v55, v55, v143
	s_waitcnt vmcnt(6)
	v_mul_f32_e32 v112, v138, v194
	v_mfma_f32_32x32x16_bf16 v[16:31], v[116:119], v[120:123], v[16:31]
	v_mul_f32_e32 v113, v138, v195
	s_waitcnt vmcnt(5)
	v_fmac_f32_e32 v112, v139, v48
	v_mul_f32_e32 v114, v138, v196
	v_mul_f32_e32 v115, v138, v197
	v_mul_f32_e32 v116, v138, v124
	v_mul_f32_e32 v117, v138, v125
	v_mul_f32_e32 v118, v138, v126
	v_fmac_f32_e32 v113, v139, v49
	s_waitcnt vmcnt(4)
	v_add_f32_e32 v48, v213, v112
	v_mul_f32_e32 v48, v48, v144
	v_cvt_pk_bf16_f32 v48, v48, s0
	v_fmac_f32_e32 v114, v139, v50
	v_fmac_f32_e32 v115, v139, v51
	v_fmac_f32_e32 v116, v139, v52
	v_fmac_f32_e32 v117, v139, v53
	v_fmac_f32_e32 v118, v139, v54
	ds_write_b16 v183, v48
	s_waitcnt vmcnt(3)
	v_add_f32_e32 v49, v210, v113
	v_add_f32_e32 v50, v211, v114
	v_add_f32_e32 v51, v212, v115
	s_waitcnt vmcnt(2)
	v_add_f32_e32 v52, v128, v116
	v_add_f32_e32 v53, v129, v117
	v_add_f32_e32 v54, v130, v118
	ds_read_u16 v48, v193
	ds_read_u16 v112, v193 offset:144
	ds_read_u16 v113, v193 offset:288
	ds_read_u16 v114, v193 offset:1008
	ds_read_u16 v115, v193 offset:1152
	ds_read_u16 v116, v193 offset:1296
	ds_read_u16 v117, v193 offset:1440
	ds_read_u16 v118, v193 offset:2160
	s_waitcnt lgkmcnt(7)
	v_lshlrev_b32_e32 v48, 16, v48
	s_waitcnt lgkmcnt(6)
	v_lshlrev_b32_e32 v112, 16, v112
	s_waitcnt lgkmcnt(5)
	v_lshlrev_b32_e32 v113, 16, v113
	s_waitcnt lgkmcnt(4)
	v_lshlrev_b32_e32 v114, 16, v114
	s_waitcnt lgkmcnt(3)
	v_lshlrev_b32_e32 v115, 16, v115
	s_waitcnt lgkmcnt(2)
	v_lshlrev_b32_e32 v116, 16, v116
	v_mul_f32_e32 v48, v49, v48
	v_mul_f32_e32 v49, v50, v112
	v_mul_f32_e32 v50, v51, v113
	v_mul_f32_e32 v51, v52, v114
	v_mul_f32_e32 v52, v53, v115
	v_mul_f32_e32 v53, v54, v116
	v_cvt_pk_bf16_f32 v48, v48, s0
	v_cvt_pk_bf16_f32 v49, v49, s0
	v_cvt_pk_bf16_f32 v50, v50, s0
	v_cvt_pk_bf16_f32 v51, v51, s0
	v_cvt_pk_bf16_f32 v52, v52, s0
	v_cvt_pk_bf16_f32 v53, v53, s0
	ds_write_b16 v193, v48
	ds_write_b16 v193, v49 offset:144
	ds_write_b16 v193, v50 offset:288
	ds_write_b16 v193, v51 offset:1008
	ds_write_b16 v193, v52 offset:1152
	ds_write_b16 v193, v53 offset:1296
	ds_read_b128 v[48:51], v185 offset:1536
	v_mul_f32_e32 v119, v138, v127
	v_fmac_f32_e32 v119, v139, v55
	v_add_f32_e32 v52, v131, v119
	s_waitcnt lgkmcnt(8)
	v_lshlrev_b32_e32 v53, 16, v117
	s_waitcnt lgkmcnt(0)
	v_sub_f32_e32 v48, v56, v48
	v_mul_f32_e32 v56, v138, v198
	v_fmac_f32_e32 v56, v139, v48
	s_waitcnt vmcnt(1)
	v_add_f32_e32 v48, v202, v56
	v_lshlrev_b32_e32 v56, 16, v118
	v_mul_f32_e32 v48, v48, v56
	v_mul_f32_e32 v52, v52, v53
	v_cvt_pk_bf16_f32 v48, v48, s0
	v_cvt_pk_bf16_f32 v52, v52, s0
	ds_write_b16 v193, v48 offset:2160
	v_sub_f32_e32 v48, v57, v49
	v_mul_f32_e32 v49, v138, v199
	ds_write_b16 v193, v52 offset:1440
	v_fmac_f32_e32 v49, v139, v48
	ds_read_b128 v[52:55], v186 offset:1024
	v_add_f32_e32 v48, v203, v49
	ds_read_u16 v49, v193 offset:2304
	ds_read_u16 v56, v193 offset:2448
	ds_read_u16 v57, v193 offset:2592
	ds_read_u16 v112, v193 offset:3312
	ds_read_u16 v113, v193 offset:3456
	ds_read_u16 v114, v193 offset:3600
	ds_read_u16 v115, v193 offset:3744
	s_waitcnt lgkmcnt(6)
	v_lshlrev_b32_e32 v49, 16, v49
	v_mul_f32_e32 v48, v48, v49
	v_cvt_pk_bf16_f32 v48, v48, s0
	ds_write_b16 v193, v48 offset:2304
	v_sub_f32_e32 v48, v58, v50
	v_mul_f32_e32 v49, v138, v200
	v_fmac_f32_e32 v49, v139, v48
	v_add_f32_e32 v48, v204, v49
	s_waitcnt lgkmcnt(6)
	v_lshlrev_b32_e32 v49, 16, v56
	v_mul_f32_e32 v48, v48, v49
	v_cvt_pk_bf16_f32 v48, v48, s0
	ds_write_b16 v193, v48 offset:2448
	v_sub_f32_e32 v48, v59, v51
	v_mul_f32_e32 v49, v138, v201
	v_fmac_f32_e32 v49, v139, v48
	v_add_f32_e32 v56, v205, v49
	ds_read_b128 v[48:51], v186 offset:1536
	v_mul_f32_e32 v52, v138, v52
	s_waitcnt lgkmcnt(7)
	v_lshlrev_b32_e32 v57, 16, v57
	v_mul_f32_e32 v56, v56, v57
	v_cvt_pk_bf16_f32 v56, v56, s0
	s_waitcnt lgkmcnt(0)
	v_sub_f32_e32 v48, v60, v48
	v_fmac_f32_e32 v52, v139, v48
	s_waitcnt vmcnt(0)
	v_add_f32_e32 v48, v206, v52
	v_lshlrev_b32_e32 v52, 16, v112
	v_mul_f32_e32 v48, v48, v52
	v_cvt_pk_bf16_f32 v48, v48, s0
	ds_write_b16 v193, v48 offset:3312
	v_sub_f32_e32 v48, v61, v49
	v_mul_f32_e32 v49, v138, v53
	v_fmac_f32_e32 v49, v139, v48
	v_add_f32_e32 v48, v207, v49
	v_lshlrev_b32_e32 v49, 16, v113
	v_mul_f32_e32 v48, v48, v49
	v_cvt_pk_bf16_f32 v48, v48, s0
	ds_write_b16 v193, v48 offset:3456
	v_sub_f32_e32 v48, v62, v50
	v_mul_f32_e32 v49, v138, v54
	v_fmac_f32_e32 v49, v139, v48
	v_add_f32_e32 v48, v208, v49
	v_lshlrev_b32_e32 v49, 16, v114
	v_mul_f32_e32 v48, v48, v49
	v_cvt_pk_bf16_f32 v48, v48, s0
	ds_write_b16 v193, v48 offset:3600
	v_sub_f32_e32 v48, v63, v51
	v_mul_f32_e32 v49, v138, v55
	v_fmac_f32_e32 v49, v139, v48
	v_add_f32_e32 v48, v209, v49
	v_lshlrev_b32_e32 v49, 16, v115
	v_mul_f32_e32 v48, v48, v49
	v_cvt_pk_bf16_f32 v48, v48, s0
	ds_write_b16 v193, v56 offset:2592
	ds_write_b16 v193, v48 offset:3744
	global_load_dwordx4 v[52:55], v[132:133], off offset:128
	v_lshl_add_u64 v[48:49], s[12:13], 0, v[158:159]
	v_lshl_add_u64 v[48:49], v[48:49], 2, s[50:51]
	global_load_dwordx4 v[56:59], v[48:49], off offset:128
	v_mfma_f32_32x32x16_bf16 v[16:31], v[108:111], v[104:107], v[16:31]
	ds_read_b128 v[60:63], v187 offset:1536
	ds_read_b128 v[108:111], v187 offset:1024
	v_lshl_add_u64 v[50:51], s[12:13], 0, v[160:161]
	v_lshl_add_u64 v[50:51], v[50:51], 2, s[50:51]
	s_waitcnt lgkmcnt(1)
	v_sub_f32_e32 v32, v32, v60
	s_waitcnt lgkmcnt(0)
	v_mul_f32_e32 v60, v138, v108
	v_fmac_f32_e32 v60, v139, v32
	v_mfma_f32_32x32x16_bf16 v[0:15], v[100:103], v[104:107], v[0:15]
	global_load_dwordx4 v[100:103], v[50:51], off offset:128
	s_waitcnt vmcnt(2)
	v_add_f32_e32 v32, v52, v60
	ds_read_u16 v52, v183 offset:4608
	ds_read_u16 v60, v183 offset:4752
	ds_read_u16 v104, v183 offset:4896
	ds_read_u16 v105, v183 offset:5040
	ds_read_u16 v108, v183 offset:5760
	ds_read_u16 v112, v183 offset:5904
	ds_read_u16 v113, v183 offset:6048
	ds_read_u16 v114, v183 offset:6192
	s_waitcnt lgkmcnt(7)
	v_lshlrev_b32_e32 v52, 16, v52
	v_mul_f32_e32 v32, v32, v52
	v_cvt_pk_bf16_f32 v32, v32, s0
	ds_write_b16 v183, v32 offset:4608
	v_sub_f32_e32 v32, v33, v61
	v_mul_f32_e32 v33, v138, v109
	v_fmac_f32_e32 v33, v139, v32
	v_add_f32_e32 v32, v53, v33
	s_waitcnt lgkmcnt(7)
	v_lshlrev_b32_e32 v33, 16, v60
	v_mul_f32_e32 v32, v32, v33
	v_cvt_pk_bf16_f32 v32, v32, s0
	ds_write_b16 v183, v32 offset:4752
	v_sub_f32_e32 v32, v34, v62
	v_mul_f32_e32 v33, v138, v110
	v_fmac_f32_e32 v33, v139, v32
	v_add_f32_e32 v32, v54, v33
	s_waitcnt lgkmcnt(7)
	v_lshlrev_b32_e32 v33, 16, v104
	v_mul_f32_e32 v32, v32, v33
	v_cvt_pk_bf16_f32 v32, v32, s0
	ds_write_b16 v183, v32 offset:4896
	v_sub_f32_e32 v32, v35, v63
	v_mul_f32_e32 v33, v138, v111
	v_fmac_f32_e32 v33, v139, v32
	v_add_f32_e32 v32, v55, v33
	s_waitcnt lgkmcnt(7)
	v_lshlrev_b32_e32 v33, 16, v105
	v_mul_f32_e32 v32, v32, v33
	v_cvt_pk_bf16_f32 v32, v32, s0
	ds_write_b16 v183, v32 offset:5040
	v_lshl_add_u64 v[32:33], s[12:13], 0, v[162:163]
	v_lshl_add_u64 v[32:33], v[32:33], 2, s[50:51]
	ds_read_b128 v[52:55], v188 offset:1536
	ds_read_b128 v[60:63], v188 offset:1024
	global_load_dwordx4 v[104:107], v[32:33], off offset:128
	v_mfma_f32_32x32x16_bf16 v[16:31], v[92:95], v[96:99], v[16:31]
	s_waitcnt lgkmcnt(1)
	v_sub_f32_e32 v34, v36, v52
	s_waitcnt lgkmcnt(0)
	v_mul_f32_e32 v35, v138, v60
	v_fmac_f32_e32 v35, v139, v34
	s_waitcnt vmcnt(2)
	v_add_f32_e32 v34, v56, v35
	v_lshlrev_b32_e32 v35, 16, v108
	v_mul_f32_e32 v34, v34, v35
	v_cvt_pk_bf16_f32 v34, v34, s0
	ds_write_b16 v183, v34 offset:5760
	v_sub_f32_e32 v34, v37, v53
	v_mul_f32_e32 v35, v138, v61
	v_fmac_f32_e32 v35, v139, v34
	v_add_f32_e32 v34, v57, v35
	v_lshlrev_b32_e32 v35, 16, v112
	v_mul_f32_e32 v34, v34, v35
	v_cvt_pk_bf16_f32 v34, v34, s0
	ds_write_b16 v183, v34 offset:5904
	v_sub_f32_e32 v34, v38, v54
	v_mul_f32_e32 v35, v138, v62
	v_fmac_f32_e32 v35, v139, v34
	v_add_f32_e32 v34, v58, v35
	v_lshlrev_b32_e32 v35, 16, v113
	v_mul_f32_e32 v34, v34, v35
	v_cvt_pk_bf16_f32 v34, v34, s0
	ds_write_b16 v183, v34 offset:6048
	v_sub_f32_e32 v34, v39, v55
	v_mul_f32_e32 v35, v138, v63
	v_fmac_f32_e32 v35, v139, v34
	v_add_f32_e32 v38, v59, v35
	ds_read_b128 v[34:37], v189 offset:1536
	ds_read_b128 v[52:55], v189 offset:1024
	v_lshlrev_b32_e32 v39, 16, v114
	v_mul_f32_e32 v38, v38, v39
	v_cvt_pk_bf16_f32 v38, v38, s0
	ds_write_b16 v183, v38 offset:6192
	s_waitcnt lgkmcnt(2)
	v_sub_f32_e32 v34, v40, v34
	s_waitcnt lgkmcnt(1)
	v_mul_f32_e32 v38, v138, v52
	v_fmac_f32_e32 v38, v139, v34
	s_waitcnt vmcnt(1)
	v_add_f32_e32 v34, v100, v38
	ds_read_u16 v38, v183 offset:6912
	ds_read_u16 v39, v183 offset:7056
	ds_read_u16 v40, v183 offset:7200
	ds_read_u16 v52, v183 offset:7344
	ds_read_u16 v56, v183 offset:8064
	ds_read_u16 v57, v183 offset:8208
	ds_read_u16 v58, v183 offset:8352
	ds_read_u16 v59, v183 offset:8496
	s_waitcnt lgkmcnt(7)
	v_lshlrev_b32_e32 v38, 16, v38
	v_mul_f32_e32 v34, v34, v38
	v_cvt_pk_bf16_f32 v34, v34, s0
	ds_write_b16 v183, v34 offset:6912
	v_sub_f32_e32 v34, v41, v35
	v_mul_f32_e32 v35, v138, v53
	v_fmac_f32_e32 v35, v139, v34
	v_add_f32_e32 v34, v101, v35
	s_waitcnt lgkmcnt(7)
	v_lshlrev_b32_e32 v35, 16, v39
	v_mul_f32_e32 v34, v34, v35
	v_cvt_pk_bf16_f32 v34, v34, s0
	ds_write_b16 v183, v34 offset:7056
	v_sub_f32_e32 v34, v42, v36
	v_mul_f32_e32 v35, v138, v54
	v_fmac_f32_e32 v35, v139, v34
	v_add_f32_e32 v34, v102, v35
	s_waitcnt lgkmcnt(7)
	v_lshlrev_b32_e32 v35, 16, v40
	v_mul_f32_e32 v34, v34, v35
	v_cvt_pk_bf16_f32 v34, v34, s0
	ds_write_b16 v183, v34 offset:7200
	v_sub_f32_e32 v34, v43, v37
	v_mul_f32_e32 v35, v138, v55
	v_fmac_f32_e32 v35, v139, v34
	v_add_f32_e32 v42, v103, v35
	ds_read_b128 v[34:37], v190 offset:1536
	ds_read_b128 v[38:41], v190 offset:1024
	s_waitcnt lgkmcnt(9)
	v_lshlrev_b32_e32 v43, 16, v52
	v_mul_f32_e32 v42, v42, v43
	v_cvt_pk_bf16_f32 v42, v42, s0
	s_waitcnt lgkmcnt(1)
	v_sub_f32_e32 v34, v44, v34
	s_waitcnt lgkmcnt(0)
	v_mul_f32_e32 v38, v138, v38
	v_fmac_f32_e32 v38, v139, v34
	ds_write_b16 v183, v42 offset:7344
	v_mfma_f32_32x32x16_bf16 v[16:31], v[84:87], v[76:79], v[16:31]
	s_waitcnt vmcnt(0)
	v_add_f32_e32 v34, v104, v38
	v_lshlrev_b32_e32 v38, 16, v56
	v_mul_f32_e32 v34, v34, v38
	v_cvt_pk_bf16_f32 v34, v34, s0
	ds_write_b16 v183, v34 offset:8064
	v_sub_f32_e32 v34, v45, v35
	v_mul_f32_e32 v35, v138, v39
	v_fmac_f32_e32 v35, v139, v34
	v_add_f32_e32 v34, v105, v35
	v_lshlrev_b32_e32 v35, 16, v57
	v_mul_f32_e32 v34, v34, v35
	v_cvt_pk_bf16_f32 v34, v34, s0
	ds_write_b16 v183, v34 offset:8208
	v_sub_f32_e32 v34, v46, v36
	v_mul_f32_e32 v35, v138, v40
	v_fmac_f32_e32 v35, v139, v34
	v_add_f32_e32 v34, v106, v35
	v_lshlrev_b32_e32 v35, 16, v58
	v_mul_f32_e32 v34, v34, v35
	v_cvt_pk_bf16_f32 v34, v34, s0
	ds_write_b16 v183, v34 offset:8352
	v_sub_f32_e32 v34, v47, v37
	v_mul_f32_e32 v35, v138, v41
	v_fmac_f32_e32 v35, v139, v34
	v_add_f32_e32 v34, v107, v35
	v_lshlrev_b32_e32 v35, 16, v59
	v_mul_f32_e32 v34, v34, v35
	v_cvt_pk_bf16_f32 v34, v34, s0
	ds_write_b16 v183, v34 offset:8496
	global_load_dword v34, v[170:171], off offset:128
	global_load_dword v35, v[136:137], off offset:128
	global_load_dword v56, v[134:135], off
	global_load_dwordx3 v[60:62], v[132:133], off offset:4
	global_load_dwordx4 v[36:39], v[132:133], off offset:32
	v_mfma_f32_32x32x16_bf16 v[16:31], v[80:83], v[68:71], v[16:31]
	ds_read_b128 v[40:43], v182 offset:1536
	ds_read_b128 v[44:47], v182 offset:1024
	global_load_dwordx4 v[52:55], v[132:133], off offset:64
	v_mfma_f32_32x32x16_bf16 v[0:15], v[88:91], v[96:99], v[0:15]
	s_waitcnt lgkmcnt(1)
	s_nop 6
	v_sub_f32_e32 v16, v16, v40
	s_waitcnt vmcnt(5) lgkmcnt(0)
	v_mul_f32_e32 v40, v34, v44
	ds_read_u16 v44, v183 offset:64
	s_waitcnt vmcnt(4)
	v_fmac_f32_e32 v40, v35, v16
	s_waitcnt vmcnt(3)
	v_add_f32_e32 v16, v56, v40
	ds_read_b128 v[56:59], v184 offset:1024
	v_mfma_f32_32x32x16_bf16 v[0:15], v[72:75], v[76:79], v[0:15]
	s_waitcnt lgkmcnt(1)
	v_lshlrev_b32_e32 v40, 16, v44
	v_mul_f32_e32 v16, v16, v40
	v_cvt_pk_bf16_f32 v16, v16, s0
	ds_write_b16 v183, v16 offset:64
	v_sub_f32_e32 v16, v17, v41
	v_mul_f32_e32 v16, v35, v16
	v_fmac_f32_e32 v16, v34, v45
	s_waitcnt vmcnt(2)
	v_add_f32_e32 v16, v60, v16
	ds_read_u16 v17, v193 offset:64
	ds_read_u16 v40, v193 offset:208
	ds_read_u16 v41, v193 offset:352
	ds_read_u16 v60, v193 offset:1072
	ds_read_u16 v63, v193 offset:1216
	ds_read_u16 v80, v193 offset:1360
	ds_read_u16 v81, v193 offset:1504
	ds_read_u16 v82, v193 offset:2224
	s_waitcnt lgkmcnt(7)
	v_lshlrev_b32_e32 v17, 16, v17
	v_mul_f32_e32 v16, v16, v17
	v_cvt_pk_bf16_f32 v16, v16, s0
	ds_write_b16 v193, v16 offset:64
	v_sub_f32_e32 v16, v18, v42
	v_mul_f32_e32 v16, v35, v16
	v_fmac_f32_e32 v16, v34, v46
	v_add_f32_e32 v16, v61, v16
	s_waitcnt lgkmcnt(7)
	v_lshlrev_b32_e32 v17, 16, v40
	v_mul_f32_e32 v16, v16, v17
	v_cvt_pk_bf16_f32 v16, v16, s0
	ds_write_b16 v193, v16 offset:208
	v_sub_f32_e32 v16, v19, v43
	v_mul_f32_e32 v16, v35, v16
	v_fmac_f32_e32 v16, v34, v47
	v_add_f32_e32 v16, v62, v16
	s_waitcnt lgkmcnt(7)
	v_lshlrev_b32_e32 v17, 16, v41
	v_mul_f32_e32 v40, v16, v17
	v_cvt_pk_bf16_f32 v44, v40, s0
	global_load_dwordx4 v[40:43], v[132:133], off offset:96
	ds_read_b128 v[16:19], v184 offset:1536
	ds_write_b16 v193, v44 offset:352
	ds_read_b128 v[44:47], v185 offset:1024
	v_mfma_f32_32x32x16_bf16 v[0:15], v[64:67], v[68:71], v[0:15]
	s_waitcnt lgkmcnt(2)
	v_sub_f32_e32 v16, v20, v16
	v_mul_f32_e32 v16, v35, v16
	v_fmac_f32_e32 v16, v34, v56
	s_waitcnt vmcnt(2)
	v_add_f32_e32 v16, v36, v16
	v_lshlrev_b32_e32 v20, 16, v60
	v_mul_f32_e32 v16, v16, v20
	v_cvt_pk_bf16_f32 v16, v16, s0
	ds_write_b16 v193, v16 offset:1072
	v_sub_f32_e32 v16, v21, v17
	v_mul_f32_e32 v16, v35, v16
	v_fmac_f32_e32 v16, v34, v57
	v_add_f32_e32 v16, v37, v16
	v_lshlrev_b32_e32 v17, 16, v63
	v_mul_f32_e32 v16, v16, v17
	v_cvt_pk_bf16_f32 v16, v16, s0
	ds_write_b16 v193, v16 offset:1216
	v_sub_f32_e32 v16, v22, v18
	v_mul_f32_e32 v16, v35, v16
	v_fmac_f32_e32 v16, v34, v58
	v_add_f32_e32 v16, v38, v16
	v_lshlrev_b32_e32 v17, 16, v80
	v_mul_f32_e32 v16, v16, v17
	v_cvt_pk_bf16_f32 v16, v16, s0
	ds_write_b16 v193, v16 offset:1360
	v_sub_f32_e32 v16, v23, v19
	v_mul_f32_e32 v16, v35, v16
	v_fmac_f32_e32 v16, v34, v59
	v_add_f32_e32 v20, v39, v16
	ds_read_b128 v[16:19], v185 offset:1536
	v_lshlrev_b32_e32 v21, 16, v81
	v_mul_f32_e32 v20, v20, v21
	v_cvt_pk_bf16_f32 v20, v20, s0
	ds_write_b16 v193, v20 offset:1504
	s_waitcnt lgkmcnt(1)
	v_sub_f32_e32 v16, v24, v16
	v_mul_f32_e32 v16, v35, v16
	v_fmac_f32_e32 v16, v34, v44
	s_waitcnt vmcnt(1)
	v_add_f32_e32 v16, v52, v16
	v_lshlrev_b32_e32 v24, 16, v82
	v_mul_f32_e32 v16, v16, v24
	v_cvt_pk_bf16_f32 v16, v16, s0
	ds_write_b16 v193, v16 offset:2224
	v_sub_f32_e32 v16, v25, v17
	v_mul_f32_e32 v16, v35, v16
	ds_read_b128 v[20:23], v186 offset:1024
	v_fmac_f32_e32 v16, v34, v45
	ds_read_u16 v17, v193 offset:2368
	ds_read_u16 v24, v193 offset:2512
	ds_read_u16 v25, v193 offset:2656
	ds_read_u16 v36, v193 offset:3376
	ds_read_u16 v37, v193 offset:3520
	ds_read_u16 v38, v193 offset:3664
	ds_read_u16 v39, v193 offset:3808
	v_add_f32_e32 v16, v53, v16
	s_waitcnt lgkmcnt(6)
	v_lshlrev_b32_e32 v17, 16, v17
	v_mul_f32_e32 v16, v16, v17
	v_cvt_pk_bf16_f32 v16, v16, s0
	ds_write_b16 v193, v16 offset:2368
	v_sub_f32_e32 v16, v26, v18
	v_mul_f32_e32 v16, v35, v16
	v_fmac_f32_e32 v16, v34, v46
	v_add_f32_e32 v16, v54, v16
	s_waitcnt lgkmcnt(6)
	v_lshlrev_b32_e32 v17, 16, v24
	v_mul_f32_e32 v16, v16, v17
	v_cvt_pk_bf16_f32 v16, v16, s0
	ds_write_b16 v193, v16 offset:2512
	v_sub_f32_e32 v16, v27, v19
	v_mul_f32_e32 v16, v35, v16
	v_fmac_f32_e32 v16, v34, v47
	v_add_f32_e32 v24, v55, v16
	ds_read_b128 v[16:19], v186 offset:1536
	s_waitcnt lgkmcnt(7)
	v_lshlrev_b32_e32 v25, 16, v25
	v_mul_f32_e32 v24, v24, v25
	v_cvt_pk_bf16_f32 v24, v24, s0
	ds_write_b16 v193, v24 offset:2656
	s_waitcnt lgkmcnt(1)
	v_sub_f32_e32 v16, v28, v16
	v_mul_f32_e32 v16, v35, v16
	v_fmac_f32_e32 v16, v34, v20
	v_lshlrev_b32_e32 v20, 16, v36
	s_waitcnt vmcnt(0)
	v_add_f32_e32 v16, v40, v16
	v_mul_f32_e32 v16, v16, v20
	v_cvt_pk_bf16_f32 v16, v16, s0
	ds_write_b16 v193, v16 offset:3376
	v_sub_f32_e32 v16, v29, v17
	v_mul_f32_e32 v16, v35, v16
	v_fmac_f32_e32 v16, v34, v21
	v_add_f32_e32 v16, v41, v16
	v_lshlrev_b32_e32 v17, 16, v37
	v_mul_f32_e32 v16, v16, v17
	v_cvt_pk_bf16_f32 v16, v16, s0
	ds_write_b16 v193, v16 offset:3520
	v_sub_f32_e32 v16, v30, v18
	v_mul_f32_e32 v16, v35, v16
	v_fmac_f32_e32 v16, v34, v22
	v_add_f32_e32 v16, v42, v16
	v_lshlrev_b32_e32 v17, 16, v38
	v_mul_f32_e32 v16, v16, v17
	v_cvt_pk_bf16_f32 v16, v16, s0
	ds_write_b16 v193, v16 offset:3664
	v_sub_f32_e32 v16, v31, v19
	v_mul_f32_e32 v16, v35, v16
	v_fmac_f32_e32 v16, v34, v23
	v_add_f32_e32 v16, v43, v16
	v_lshlrev_b32_e32 v17, 16, v39
	v_mul_f32_e32 v16, v16, v17
	v_cvt_pk_bf16_f32 v16, v16, s0
	ds_write_b16 v193, v16 offset:3808
	global_load_dwordx4 v[16:19], v[132:133], off offset:128
	global_load_dwordx4 v[20:23], v[48:49], off offset:128
	ds_read_b128 v[24:27], v187 offset:1536
	ds_read_b128 v[28:31], v187 offset:1024
	global_load_dwordx4 v[36:39], v[50:51], off offset:128
	s_waitcnt lgkmcnt(1)
	v_sub_f32_e32 v0, v0, v24
	s_waitcnt lgkmcnt(0)
	v_mul_f32_e32 v24, v34, v28
	v_fmac_f32_e32 v24, v35, v0
	s_waitcnt vmcnt(2)
	v_add_f32_e32 v0, v16, v24
	ds_read_u16 v16, v183 offset:4672
	ds_read_u16 v24, v183 offset:4816
	ds_read_u16 v28, v183 offset:4960
	ds_read_u16 v40, v183 offset:5104
	ds_read_u16 v41, v183 offset:5824
	ds_read_u16 v42, v183 offset:5968
	ds_read_u16 v43, v183 offset:6112
	ds_read_u16 v44, v183 offset:6256
	s_waitcnt lgkmcnt(7)
	v_lshlrev_b32_e32 v16, 16, v16
	v_mul_f32_e32 v0, v0, v16
	v_cvt_pk_bf16_f32 v0, v0, s0
	ds_write_b16 v183, v0 offset:4672
	v_sub_f32_e32 v0, v1, v25
	v_mul_f32_e32 v0, v35, v0
	v_fmac_f32_e32 v0, v34, v29
	v_add_f32_e32 v0, v17, v0
	s_waitcnt lgkmcnt(7)
	v_lshlrev_b32_e32 v1, 16, v24
	v_mul_f32_e32 v0, v0, v1
	v_cvt_pk_bf16_f32 v0, v0, s0
	ds_write_b16 v183, v0 offset:4816
	v_sub_f32_e32 v0, v2, v26
	v_mul_f32_e32 v0, v35, v0
	v_fmac_f32_e32 v0, v34, v30
	v_add_f32_e32 v0, v18, v0
	s_waitcnt lgkmcnt(7)
	v_lshlrev_b32_e32 v1, 16, v28
	v_mul_f32_e32 v0, v0, v1
	v_cvt_pk_bf16_f32 v0, v0, s0
	ds_write_b16 v183, v0 offset:4960
	v_sub_f32_e32 v0, v3, v27
	v_mul_f32_e32 v0, v35, v0
	v_fmac_f32_e32 v0, v34, v31
	v_add_f32_e32 v24, v19, v0
	s_waitcnt lgkmcnt(7)
	v_lshlrev_b32_e32 v25, 16, v40
	v_mul_f32_e32 v24, v24, v25
	v_cvt_pk_bf16_f32 v24, v24, s0
	ds_read_b128 v[0:3], v188 offset:1024
	ds_read_b128 v[16:19], v188 offset:1536
	ds_write_b16 v183, v24 offset:5104
	global_load_dwordx4 v[24:27], v[32:33], off offset:128
	s_waitcnt lgkmcnt(1)
	v_sub_f32_e32 v4, v4, v16
	v_mul_f32_e32 v4, v35, v4
	v_fmac_f32_e32 v4, v34, v0
	s_waitcnt vmcnt(2)
	v_add_f32_e32 v0, v20, v4
	v_lshlrev_b32_e32 v4, 16, v41
	v_mul_f32_e32 v0, v0, v4
	v_cvt_pk_bf16_f32 v0, v0, s0
	ds_write_b16 v183, v0 offset:5824
	v_sub_f32_e32 v0, v5, v17
	v_mul_f32_e32 v0, v35, v0
	v_fmac_f32_e32 v0, v34, v1
	v_add_f32_e32 v0, v21, v0
	v_lshlrev_b32_e32 v1, 16, v42
	v_mul_f32_e32 v0, v0, v1
	v_cvt_pk_bf16_f32 v0, v0, s0
	ds_write_b16 v183, v0 offset:5968
	v_sub_f32_e32 v0, v6, v18
	v_mul_f32_e32 v0, v35, v0
	v_fmac_f32_e32 v0, v34, v2
	v_add_f32_e32 v0, v22, v0
	v_lshlrev_b32_e32 v1, 16, v43
	v_mul_f32_e32 v0, v0, v1
	v_cvt_pk_bf16_f32 v0, v0, s0
	ds_write_b16 v183, v0 offset:6112
	v_sub_f32_e32 v0, v7, v19
	v_mul_f32_e32 v0, v35, v0
	v_fmac_f32_e32 v0, v34, v3
	v_add_f32_e32 v16, v23, v0
	ds_read_b128 v[0:3], v189 offset:1024
	ds_read_b128 v[4:7], v189 offset:1536
	v_lshlrev_b32_e32 v17, 16, v44
	v_mul_f32_e32 v16, v16, v17
	v_cvt_pk_bf16_f32 v16, v16, s0
	ds_write_b16 v183, v16 offset:6256
	s_waitcnt lgkmcnt(1)
	v_sub_f32_e32 v4, v8, v4
	v_mul_f32_e32 v4, v35, v4
	v_fmac_f32_e32 v4, v34, v0
	s_waitcnt vmcnt(1)
	v_add_f32_e32 v0, v36, v4
	ds_read_u16 v4, v183 offset:6976
	ds_read_u16 v8, v183 offset:7120
	ds_read_u16 v16, v183 offset:7264
	ds_read_u16 v17, v183 offset:7408
	ds_read_u16 v18, v183 offset:8128
	ds_read_u16 v19, v183 offset:8272
	ds_read_u16 v20, v183 offset:8416
	ds_read_u16 v21, v183 offset:8560
	s_waitcnt lgkmcnt(7)
	v_lshlrev_b32_e32 v4, 16, v4
	v_mul_f32_e32 v0, v0, v4
	v_cvt_pk_bf16_f32 v0, v0, s0
	ds_write_b16 v183, v0 offset:6976
	v_sub_f32_e32 v0, v9, v5
	v_mul_f32_e32 v0, v35, v0
	v_fmac_f32_e32 v0, v34, v1
	v_add_f32_e32 v0, v37, v0
	s_waitcnt lgkmcnt(7)
	v_lshlrev_b32_e32 v1, 16, v8
	v_mul_f32_e32 v0, v0, v1
	v_cvt_pk_bf16_f32 v0, v0, s0
	ds_write_b16 v183, v0 offset:7120
	v_sub_f32_e32 v0, v10, v6
	v_mul_f32_e32 v0, v35, v0
	v_fmac_f32_e32 v0, v34, v2
	v_add_f32_e32 v0, v38, v0
	s_waitcnt lgkmcnt(7)
	v_lshlrev_b32_e32 v1, 16, v16
	v_mul_f32_e32 v0, v0, v1
	v_cvt_pk_bf16_f32 v0, v0, s0
	ds_write_b16 v183, v0 offset:7264
	v_sub_f32_e32 v0, v11, v7
	v_mul_f32_e32 v0, v35, v0
	v_fmac_f32_e32 v0, v34, v3
	v_add_f32_e32 v8, v39, v0
	ds_read_b128 v[0:3], v190 offset:1024
	ds_read_b128 v[4:7], v190 offset:1536
	s_waitcnt lgkmcnt(9)
	v_lshlrev_b32_e32 v9, 16, v17
	v_mul_f32_e32 v8, v8, v9
	v_cvt_pk_bf16_f32 v8, v8, s0
	ds_write_b16 v183, v8 offset:7408
	s_waitcnt lgkmcnt(1)
	v_sub_f32_e32 v4, v12, v4
	v_mul_f32_e32 v4, v35, v4
	v_fmac_f32_e32 v4, v34, v0
	s_waitcnt vmcnt(0)
	v_add_f32_e32 v0, v24, v4
	v_lshlrev_b32_e32 v4, 16, v18
	v_mul_f32_e32 v0, v0, v4
	v_cvt_pk_bf16_f32 v0, v0, s0
	ds_write_b16 v183, v0 offset:8128
	v_sub_f32_e32 v0, v13, v5
	v_mul_f32_e32 v0, v35, v0
	v_fmac_f32_e32 v0, v34, v1
	v_add_f32_e32 v0, v25, v0
	v_lshlrev_b32_e32 v1, 16, v19
	v_mul_f32_e32 v0, v0, v1
	v_cvt_pk_bf16_f32 v0, v0, s0
	ds_write_b16 v183, v0 offset:8272
	v_sub_f32_e32 v0, v14, v6
	v_mul_f32_e32 v0, v35, v0
	v_fmac_f32_e32 v0, v34, v2
	v_add_f32_e32 v0, v26, v0
	v_lshlrev_b32_e32 v1, 16, v20
	v_mul_f32_e32 v0, v0, v1
	v_cvt_pk_bf16_f32 v0, v0, s0
	ds_write_b16 v183, v0 offset:8416
	v_sub_f32_e32 v0, v15, v7
	v_mul_f32_e32 v0, v35, v0
	v_fmac_f32_e32 v0, v34, v3
	v_add_f32_e32 v0, v27, v0
	v_lshlrev_b32_e32 v1, 16, v21
	v_mul_f32_e32 v0, v0, v1
	v_cvt_pk_bf16_f32 v0, v0, s0
	ds_write_b16 v183, v0 offset:8560
	s_waitcnt lgkmcnt(0)
	v_mov_b32_e32 v0, v192

.LBB0_1563:
	s_ashr_i32 s10, s26, 4
	s_and_b32 s14, s26, 7
	s_and_b32 s15, s10, 0x7ffffff8
	s_or_b32 s14, s15, s14
	s_lshl_b32 s14, s14, 1
	s_bfe_u32 s15, s26, 0x10006
	s_or_b32 s14, s14, s15
	s_waitcnt vmcnt(63) expcnt(7) lgkmcnt(15)
	s_barrier
	s_and_saveexec_b64 s[16:17], s[0:1]
	s_cbranch_execz .LBB0_1565
	v_lshl_add_u32 v0, s14, 7, v153
	v_ashrrev_i32_e32 v1, 31, v0
	v_lshlrev_b64 v[0:1], 8, v[0:1]
	v_lshl_add_u64 v[60:61], s[8:9], 0, v[0:1]
	global_load_dwordx4 v[0:3], v[60:61], off nt
	global_load_dwordx4 v[4:7], v[60:61], off offset:16
	global_load_dwordx4 v[8:11], v[60:61], off offset:32
	global_load_dwordx4 v[12:15], v[60:61], off offset:48
	global_load_dwordx4 v[16:19], v[60:61], off offset:64
	global_load_dwordx4 v[20:23], v[60:61], off offset:80
	global_load_dwordx4 v[24:27], v[60:61], off offset:96
	global_load_dwordx4 v[28:31], v[60:61], off offset:112
	global_load_dwordx4 v[32:35], v[60:61], off offset:128
	global_load_dwordx4 v[36:39], v[60:61], off offset:144
	global_load_dwordx4 v[40:43], v[60:61], off offset:160
	global_load_dwordx4 v[44:47], v[60:61], off offset:176
	global_load_dwordx4 v[48:51], v[60:61], off offset:192
	global_load_dwordx4 v[52:55], v[60:61], off offset:208
	global_load_dwordx4 v[56:59], v[60:61], off offset:224
	s_nop 0
	global_load_dwordx4 v[60:63], v[60:61], off offset:240
	s_waitcnt vmcnt(15)
	v_pk_add_f32 v[0:1], v[0:1], 0 op_sel_hi:[1,0]
	s_nop 0
	v_pk_add_f32 v[0:1], v[0:1], v[2:3]
	s_waitcnt vmcnt(14)
	v_pk_add_f32 v[0:1], v[0:1], v[4:5]
	s_nop 0
	v_pk_add_f32 v[0:1], v[0:1], v[6:7]
	s_waitcnt vmcnt(13)
	v_pk_add_f32 v[0:1], v[0:1], v[8:9]
	s_nop 0
	v_pk_add_f32 v[0:1], v[0:1], v[10:11]
	s_waitcnt vmcnt(12)
	v_pk_add_f32 v[0:1], v[0:1], v[12:13]
	s_nop 0
	v_pk_add_f32 v[0:1], v[0:1], v[14:15]
	s_waitcnt vmcnt(11)
	v_pk_add_f32 v[0:1], v[0:1], v[16:17]
	s_nop 0
	v_pk_add_f32 v[0:1], v[0:1], v[18:19]
	s_waitcnt vmcnt(10)
	v_pk_add_f32 v[0:1], v[0:1], v[20:21]
	s_nop 0
	v_pk_add_f32 v[0:1], v[0:1], v[22:23]
	s_waitcnt vmcnt(9)
	v_pk_add_f32 v[0:1], v[0:1], v[24:25]
	s_nop 0
	v_pk_add_f32 v[0:1], v[0:1], v[26:27]
	s_waitcnt vmcnt(8)
	v_pk_add_f32 v[0:1], v[0:1], v[28:29]
	s_nop 0
	v_pk_add_f32 v[0:1], v[0:1], v[30:31]
	s_waitcnt vmcnt(7)
	v_pk_add_f32 v[0:1], v[0:1], v[32:33]
	s_nop 0
	v_pk_add_f32 v[0:1], v[0:1], v[34:35]
	s_waitcnt vmcnt(6)
	v_pk_add_f32 v[0:1], v[0:1], v[36:37]
	s_nop 0
	v_pk_add_f32 v[0:1], v[0:1], v[38:39]
	s_waitcnt vmcnt(5)
	v_pk_add_f32 v[0:1], v[0:1], v[40:41]
	s_nop 0
	v_pk_add_f32 v[0:1], v[0:1], v[42:43]
	s_waitcnt vmcnt(4)
	v_pk_add_f32 v[0:1], v[0:1], v[44:45]
	s_nop 0
	v_pk_add_f32 v[0:1], v[0:1], v[46:47]
	s_waitcnt vmcnt(3)
	v_pk_add_f32 v[0:1], v[0:1], v[48:49]
	s_nop 0
	v_pk_add_f32 v[0:1], v[0:1], v[50:51]
	s_waitcnt vmcnt(2)
	v_pk_add_f32 v[0:1], v[0:1], v[52:53]
	s_nop 0
	v_pk_add_f32 v[0:1], v[0:1], v[54:55]
	s_waitcnt vmcnt(1)
	v_pk_add_f32 v[0:1], v[0:1], v[56:57]
	s_nop 0
	v_pk_add_f32 v[0:1], v[0:1], v[58:59]
	s_waitcnt vmcnt(0)
	v_pk_add_f32 v[0:1], v[0:1], v[60:61]
	s_nop 0
	v_pk_add_f32 v[0:1], v[0:1], v[62:63]
	s_nop 0
	v_pk_mul_f32 v[0:1], v[0:1], s[12:13] op_sel_hi:[1,0]
	s_nop 0
	v_fma_f32 v1, -v0, v0, v1
	v_max_f32_e32 v1, 0, v1
	v_add_f32_e32 v1, 0x358637bd, v1
	v_mul_f32_e32 v2, 0x4b800000, v1
	v_cmp_gt_f32_e32 vcc, s22, v1
	s_nop 1
	v_cndmask_b32_e32 v1, v1, v2, vcc
	v_rsq_f32_e32 v1, v1
	s_nop 0
	v_mul_f32_e32 v2, 0x45800000, v1
	v_cndmask_b32_e32 v1, v1, v2, vcc
	ds_write2st64_b32 v172, v0, v1 offset1:2

.LBB0_1572:
	v_add_u32_e32 v0, s18, v153
	v_ashrrev_i32_e32 v8, 4, v0
	v_add_u32_e32 v0, 0x200, v0
	v_ashrrev_i32_e32 v9, 31, v8
	v_ashrrev_i32_e32 v10, 4, v0
	s_waitcnt lgkmcnt(1)
	v_lshl_add_u64 v[0:1], s[14:15], 0, v[8:9]
	v_ashrrev_i32_e32 v11, 31, v10
	v_lshlrev_b64 v[0:1], 8, v[0:1]
	s_waitcnt lgkmcnt(0)
	v_lshl_add_u64 v[2:3], s[14:15], 0, v[10:11]
	v_lshl_add_u64 v[12:13], v[150:151], 0, v[0:1]
	v_lshlrev_b64 v[0:1], 8, v[2:3]
	v_lshl_add_u64 v[14:15], v[150:151], 0, v[0:1]
	global_load_dwordx4 v[0:3], v[12:13], off nt
	global_load_dwordx4 v[4:7], v[14:15], off nt
	s_addk_i32 s18, 0x400
	s_cmpk_eq_i32 s18, 0x1000
	v_mad_u64_u32 v[8:9], s[20:21], v8, s13, v[152:153]
	v_mad_u64_u32 v[10:11], s[20:21], v10, s13, v[152:153]
	s_waitcnt vmcnt(1)
	ds_write_b128 v8, v[0:3] offset:18432
	s_waitcnt vmcnt(0)
	ds_write_b128 v10, v[4:7] offset:18432
	s_cbranch_scc0 .LBB0_1572
	s_waitcnt lgkmcnt(0)
	s_barrier
	ds_read_b128 v[0:3], v154
	ds_read_b128 v[8:11], v155 offset:18432
	ds_read_b128 v[136:139], v154 offset:32
	ds_read_b128 v[12:15], v155 offset:18464
	ds_read_b128 v[4:7], v154 offset:4608
	ds_read_b128 v[132:135], v154 offset:4640
	s_waitcnt lgkmcnt(4)
	v_mfma_f32_32x32x16_bf16 v[48:63], v[0:3], v[8:11], 0
	s_and_b32 s14, s23, 7
	s_lshl_b32 s10, s10, 1
	s_lshl_b32 s14, s14, 1
	s_and_b32 s10, s10, 0x1fffff0
	s_and_b32 s15, s27, 1
	s_or_b32 s10, s10, s14
	s_or_b32 s10, s10, s15
	s_waitcnt lgkmcnt(1)
	v_mfma_f32_32x32x16_bf16 v[32:47], v[4:7], v[8:11], 0
	s_mov_b64 s[14:15], 0
	v_mfma_f32_32x32x16_bf16 v[48:63], v[136:139], v[12:15], v[48:63]
	s_waitcnt lgkmcnt(0)
	v_mfma_f32_32x32x16_bf16 v[32:47], v[132:135], v[12:15], v[32:47]
	ds_read_b128 v[128:131], v154 offset:64
	ds_read_b128 v[8:11], v155 offset:18496
	ds_read_b128 v[116:119], v154 offset:96
	ds_read_b128 v[12:15], v155 offset:18528
	ds_read_b128 v[124:127], v154 offset:4672
	ds_read_b128 v[112:115], v154 offset:4704
	s_waitcnt lgkmcnt(4)
	v_mfma_f32_32x32x16_bf16 v[48:63], v[128:131], v[8:11], v[48:63]
	s_waitcnt lgkmcnt(1)
	v_mfma_f32_32x32x16_bf16 v[32:47], v[124:127], v[8:11], v[32:47]
	v_mfma_f32_32x32x16_bf16 v[48:63], v[116:119], v[12:15], v[48:63]
	s_waitcnt lgkmcnt(0)
	v_mfma_f32_32x32x16_bf16 v[32:47], v[112:115], v[12:15], v[32:47]
	ds_read_b128 v[108:111], v154 offset:55296
	ds_read_b128 v[8:11], v180
	ds_read_b128 v[12:15], v180 offset:32
	ds_read_b128 v[92:95], v154 offset:55328
	ds_read_b128 v[100:103], v154 offset:59904
	ds_read_b128 v[88:91], v154 offset:59936
	ds_read_b128 v[84:87], v154 offset:55360
	s_waitcnt lgkmcnt(5)
	v_mfma_f32_32x32x16_bf16 v[48:63], v[108:111], v[8:11], v[48:63]
	s_waitcnt lgkmcnt(2)
	v_mfma_f32_32x32x16_bf16 v[32:47], v[100:103], v[8:11], v[32:47]
	v_mfma_f32_32x32x16_bf16 v[48:63], v[92:95], v[12:15], v[48:63]
	s_waitcnt lgkmcnt(1)
	v_mfma_f32_32x32x16_bf16 v[32:47], v[88:91], v[12:15], v[32:47]
	ds_read_b128 v[12:15], v180 offset:64
	ds_read_b128 v[72:75], v154 offset:59968
	ds_read_b128 v[80:83], v154 offset:55392
	ds_read_b128 v[16:19], v180 offset:96
	ds_read_b128 v[8:11], v155 offset:23040
	ds_read_b128 v[144:147], v155 offset:23072
	ds_read_b128 v[140:143], v155 offset:23104
	ds_read_b128 v[120:123], v155 offset:23136
	ds_read_b128 v[104:107], v180 offset:4608
	ds_read_b128 v[96:99], v180 offset:4640
	ds_read_b128 v[64:67], v154 offset:60000
	ds_read_b128 v[76:79], v180 offset:4672
	ds_read_b128 v[68:71], v180 offset:4704
	s_waitcnt lgkmcnt(0)
	s_barrier
	v_mfma_f32_32x32x16_bf16 v[48:63], v[84:87], v[12:15], v[48:63]
	v_mfma_f32_32x32x16_bf16 v[32:47], v[72:75], v[12:15], v[32:47]
	v_lshl_add_u32 v12, s10, 7, v178
	v_ashrrev_i32_e32 v13, 31, v12
	v_lshlrev_b64 v[12:13], 12, v[12:13]
	v_lshl_or_b32 v12, s16, 9, v12
	v_lshl_add_u64 v[168:169], v[166:167], 0, v[12:13]
	v_mov_b32_e32 v12, v192
	v_mfma_f32_32x32x16_bf16 v[48:63], v[80:83], v[16:19], v[48:63]
	v_mfma_f32_32x32x16_bf16 v[32:47], v[64:67], v[16:19], v[32:47]
.LBB0_1574:
	v_lshl_add_u64 v[22:23], v[168:169], 0, s[14:15]
	v_add_co_u32_e32 v14, vcc, 0x6000000, v22
	s_add_u32 s14, s14, 0x20000
	s_nop 0
	v_addc_co_u32_e32 v15, vcc, 0, v23, vcc
	v_add_co_u32_e32 v18, vcc, 0x6008000, v22
	s_addc_u32 s15, s15, 0
	s_nop 0
	v_addc_co_u32_e32 v19, vcc, 0, v23, vcc
	v_add_co_u32_e32 v24, vcc, 0x6010000, v22
	global_load_dwordx4 v[14:17], v[14:15], off nt
	s_nop 0
	global_load_dwordx4 v[18:21], v[18:19], off nt
	v_addc_co_u32_e32 v25, vcc, 0, v23, vcc
	v_add_co_u32_e32 v26, vcc, 0x6018000, v22
	s_cmp_lg_u32 s14, 0x40000
	s_nop 0
	v_addc_co_u32_e32 v27, vcc, 0, v23, vcc
	global_load_dwordx4 v[22:25], v[24:25], off nt
	s_nop 0
	global_load_dwordx4 v[26:29], v[26:27], off nt
	s_waitcnt vmcnt(3)
	ds_write_b128 v12, v[14:17]
	s_waitcnt vmcnt(2)
	ds_write_b128 v12, v[18:21] offset:1152
	s_waitcnt vmcnt(1)
	ds_write_b128 v12, v[22:25] offset:2304
	s_waitcnt vmcnt(0)
	ds_write_b128 v12, v[26:29] offset:3456
	v_add_u32_e32 v12, 0x1200, v12
	s_cbranch_scc1 .LBB0_1574
	v_mfma_f32_32x32x16_bf16 v[16:31], v[0:3], v[8:11], 0
	v_add_u32_e32 v170, s17, v179
	v_ashrrev_i32_e32 v171, 31, v170
	v_lshlrev_b64 v[194:195], 2, v[170:171]
	v_lshl_add_u64 v[170:171], s[24:25], 0, v[194:195]
	s_lshl_b32 s10, s16, 7
	s_waitcnt lgkmcnt(0)
	s_mov_b64 s[14:15], 0
	v_mfma_f32_32x32x16_bf16 v[0:15], v[4:7], v[8:11], 0
	v_mfma_f32_32x32x16_bf16 v[16:31], v[136:139], v[144:147], v[16:31]
	global_load_dword v138, v[170:171], off
	v_lshl_add_u64 v[136:137], s[54:55], 0, v[194:195]
	v_add_u32_e32 v194, s10, v156
	global_load_dword v139, v[136:137], off
	v_ashrrev_i32_e32 v195, 31, v194
	v_mfma_f32_32x32x16_bf16 v[0:15], v[132:135], v[144:147], v[0:15]
	v_lshl_add_u64 v[134:135], v[194:195], 2, s[28:29]
	v_lshl_add_u64 v[132:133], s[10:11], 0, v[156:157]
	v_lshl_add_u64 v[132:133], v[132:133], 2, s[28:29]
	global_load_dword v213, v[134:135], off
	global_load_dwordx3 v[210:212], v[132:133], off offset:4
	v_mfma_f32_32x32x16_bf16 v[16:31], v[128:131], v[140:143], v[16:31]
	global_load_dwordx4 v[128:131], v[132:133], off offset:32
	ds_read_b128 v[144:147], v182 offset:1536
	ds_read_b128 v[194:197], v182 offset:1024
	s_waitcnt lgkmcnt(1)
	v_sub_f32_e32 v48, v48, v144
	v_sub_f32_e32 v49, v49, v145
	v_mfma_f32_32x32x16_bf16 v[0:15], v[124:127], v[140:143], v[0:15]
	ds_read_u16 v214, v183
	ds_read_b128 v[124:127], v184 offset:1024
	ds_read_b128 v[140:143], v184 offset:1536
	ds_read_b128 v[198:201], v185 offset:1024
	global_load_dwordx4 v[202:205], v[132:133], off offset:64
	global_load_dwordx4 v[206:209], v[132:133], off offset:96
	s_waitcnt lgkmcnt(3)
	v_lshlrev_b32_e32 v144, 16, v214
	v_sub_f32_e32 v50, v50, v146
	v_sub_f32_e32 v51, v51, v147
	s_waitcnt lgkmcnt(1)
	v_sub_f32_e32 v52, v52, v140
	v_sub_f32_e32 v53, v53, v141
	v_mfma_f32_32x32x16_bf16 v[0:15], v[112:115], v[120:123], v[0:15]
	v_sub_f32_e32 v54, v54, v142
	v_sub_f32_e32 v55, v55, v143
	s_waitcnt vmcnt(6)
	v_mul_f32_e32 v112, v138, v194
	v_mfma_f32_32x32x16_bf16 v[16:31], v[116:119], v[120:123], v[16:31]
	v_mul_f32_e32 v113, v138, v195
	s_waitcnt vmcnt(5)
	v_fmac_f32_e32 v112, v139, v48
	v_mul_f32_e32 v114, v138, v196
	v_mul_f32_e32 v115, v138, v197
	v_mul_f32_e32 v116, v138, v124
	v_mul_f32_e32 v117, v138, v125
	v_mul_f32_e32 v118, v138, v126
	v_fmac_f32_e32 v113, v139, v49
	s_waitcnt vmcnt(4)
	v_add_f32_e32 v48, v213, v112
	v_mul_f32_e32 v48, v48, v144
	v_cvt_pk_bf16_f32 v48, v48, s0
	v_fmac_f32_e32 v114, v139, v50
	v_fmac_f32_e32 v115, v139, v51
	v_fmac_f32_e32 v116, v139, v52
	v_fmac_f32_e32 v117, v139, v53
	v_fmac_f32_e32 v118, v139, v54
	ds_write_b16 v183, v48
	s_waitcnt vmcnt(3)
	v_add_f32_e32 v49, v210, v113
	v_add_f32_e32 v50, v211, v114
	v_add_f32_e32 v51, v212, v115
	s_waitcnt vmcnt(2)
	v_add_f32_e32 v52, v128, v116
	v_add_f32_e32 v53, v129, v117
	v_add_f32_e32 v54, v130, v118
	ds_read_u16 v48, v193
	ds_read_u16 v112, v193 offset:144
	ds_read_u16 v113, v193 offset:288
	ds_read_u16 v114, v193 offset:1008
	ds_read_u16 v115, v193 offset:1152
	ds_read_u16 v116, v193 offset:1296
	ds_read_u16 v117, v193 offset:1440
	ds_read_u16 v118, v193 offset:2160
	s_waitcnt lgkmcnt(7)
	v_lshlrev_b32_e32 v48, 16, v48
	s_waitcnt lgkmcnt(6)
	v_lshlrev_b32_e32 v112, 16, v112
	s_waitcnt lgkmcnt(5)
	v_lshlrev_b32_e32 v113, 16, v113
	s_waitcnt lgkmcnt(4)
	v_lshlrev_b32_e32 v114, 16, v114
	s_waitcnt lgkmcnt(3)
	v_lshlrev_b32_e32 v115, 16, v115
	s_waitcnt lgkmcnt(2)
	v_lshlrev_b32_e32 v116, 16, v116
	v_mul_f32_e32 v48, v49, v48
	v_mul_f32_e32 v49, v50, v112
	v_mul_f32_e32 v50, v51, v113
	v_mul_f32_e32 v51, v52, v114
	v_mul_f32_e32 v52, v53, v115
	v_mul_f32_e32 v53, v54, v116
	v_cvt_pk_bf16_f32 v48, v48, s0
	v_cvt_pk_bf16_f32 v49, v49, s0
	v_cvt_pk_bf16_f32 v50, v50, s0
	v_cvt_pk_bf16_f32 v51, v51, s0
	v_cvt_pk_bf16_f32 v52, v52, s0
	v_cvt_pk_bf16_f32 v53, v53, s0
	ds_write_b16 v193, v48
	ds_write_b16 v193, v49 offset:144
	ds_write_b16 v193, v50 offset:288
	ds_write_b16 v193, v51 offset:1008
	ds_write_b16 v193, v52 offset:1152
	ds_write_b16 v193, v53 offset:1296
	ds_read_b128 v[48:51], v185 offset:1536
	v_mul_f32_e32 v119, v138, v127
	v_fmac_f32_e32 v119, v139, v55
	v_add_f32_e32 v52, v131, v119
	s_waitcnt lgkmcnt(8)
	v_lshlrev_b32_e32 v53, 16, v117
	s_waitcnt lgkmcnt(0)
	v_sub_f32_e32 v48, v56, v48
	v_mul_f32_e32 v56, v138, v198
	v_fmac_f32_e32 v56, v139, v48
	s_waitcnt vmcnt(1)
	v_add_f32_e32 v48, v202, v56
	v_lshlrev_b32_e32 v56, 16, v118
	v_mul_f32_e32 v48, v48, v56
	v_mul_f32_e32 v52, v52, v53
	v_cvt_pk_bf16_f32 v48, v48, s0
	v_cvt_pk_bf16_f32 v52, v52, s0
	ds_write_b16 v193, v48 offset:2160
	v_sub_f32_e32 v48, v57, v49
	v_mul_f32_e32 v49, v138, v199
	ds_write_b16 v193, v52 offset:1440
	v_fmac_f32_e32 v49, v139, v48
	ds_read_b128 v[52:55], v186 offset:1024
	v_add_f32_e32 v48, v203, v49
	ds_read_u16 v49, v193 offset:2304
	ds_read_u16 v56, v193 offset:2448
	ds_read_u16 v57, v193 offset:2592
	ds_read_u16 v112, v193 offset:3312
	ds_read_u16 v113, v193 offset:3456
	ds_read_u16 v114, v193 offset:3600
	ds_read_u16 v115, v193 offset:3744
	s_waitcnt lgkmcnt(6)
	v_lshlrev_b32_e32 v49, 16, v49
	v_mul_f32_e32 v48, v48, v49
	v_cvt_pk_bf16_f32 v48, v48, s0
	ds_write_b16 v193, v48 offset:2304
	v_sub_f32_e32 v48, v58, v50
	v_mul_f32_e32 v49, v138, v200
	v_fmac_f32_e32 v49, v139, v48
	v_add_f32_e32 v48, v204, v49
	s_waitcnt lgkmcnt(6)
	v_lshlrev_b32_e32 v49, 16, v56
	v_mul_f32_e32 v48, v48, v49
	v_cvt_pk_bf16_f32 v48, v48, s0
	ds_write_b16 v193, v48 offset:2448
	v_sub_f32_e32 v48, v59, v51
	v_mul_f32_e32 v49, v138, v201
	v_fmac_f32_e32 v49, v139, v48
	v_add_f32_e32 v56, v205, v49
	ds_read_b128 v[48:51], v186 offset:1536
	v_mul_f32_e32 v52, v138, v52
	s_waitcnt lgkmcnt(7)
	v_lshlrev_b32_e32 v57, 16, v57
	v_mul_f32_e32 v56, v56, v57
	v_cvt_pk_bf16_f32 v56, v56, s0
	s_waitcnt lgkmcnt(0)
	v_sub_f32_e32 v48, v60, v48
	v_fmac_f32_e32 v52, v139, v48
	s_waitcnt vmcnt(0)
	v_add_f32_e32 v48, v206, v52
	v_lshlrev_b32_e32 v52, 16, v112
	v_mul_f32_e32 v48, v48, v52
	v_cvt_pk_bf16_f32 v48, v48, s0
	ds_write_b16 v193, v48 offset:3312
	v_sub_f32_e32 v48, v61, v49
	v_mul_f32_e32 v49, v138, v53
	v_fmac_f32_e32 v49, v139, v48
	v_add_f32_e32 v48, v207, v49
	v_lshlrev_b32_e32 v49, 16, v113
	v_mul_f32_e32 v48, v48, v49
	v_cvt_pk_bf16_f32 v48, v48, s0
	ds_write_b16 v193, v48 offset:3456
	v_sub_f32_e32 v48, v62, v50
	v_mul_f32_e32 v49, v138, v54
	v_fmac_f32_e32 v49, v139, v48
	v_add_f32_e32 v48, v208, v49
	v_lshlrev_b32_e32 v49, 16, v114
	v_mul_f32_e32 v48, v48, v49
	v_cvt_pk_bf16_f32 v48, v48, s0
	ds_write_b16 v193, v48 offset:3600
	v_sub_f32_e32 v48, v63, v51
	v_mul_f32_e32 v49, v138, v55
	v_fmac_f32_e32 v49, v139, v48
	v_add_f32_e32 v48, v209, v49
	v_lshlrev_b32_e32 v49, 16, v115
	v_mul_f32_e32 v48, v48, v49
	v_cvt_pk_bf16_f32 v48, v48, s0
	ds_write_b16 v193, v56 offset:2592
	ds_write_b16 v193, v48 offset:3744
	global_load_dwordx4 v[52:55], v[132:133], off offset:128
	v_lshl_add_u64 v[48:49], s[10:11], 0, v[158:159]
	v_lshl_add_u64 v[48:49], v[48:49], 2, s[28:29]
	global_load_dwordx4 v[56:59], v[48:49], off offset:128
	v_mfma_f32_32x32x16_bf16 v[16:31], v[108:111], v[104:107], v[16:31]
	ds_read_b128 v[60:63], v187 offset:1536
	ds_read_b128 v[108:111], v187 offset:1024
	v_lshl_add_u64 v[50:51], s[10:11], 0, v[160:161]
	v_lshl_add_u64 v[50:51], v[50:51], 2, s[28:29]
	s_waitcnt lgkmcnt(1)
	v_sub_f32_e32 v32, v32, v60
	s_waitcnt lgkmcnt(0)
	v_mul_f32_e32 v60, v138, v108
	v_fmac_f32_e32 v60, v139, v32
	v_mfma_f32_32x32x16_bf16 v[0:15], v[100:103], v[104:107], v[0:15]
	global_load_dwordx4 v[100:103], v[50:51], off offset:128
	s_waitcnt vmcnt(2)
	v_add_f32_e32 v32, v52, v60
	ds_read_u16 v52, v183 offset:4608
	ds_read_u16 v60, v183 offset:4752
	ds_read_u16 v104, v183 offset:4896
	ds_read_u16 v105, v183 offset:5040
	ds_read_u16 v108, v183 offset:5760
	ds_read_u16 v112, v183 offset:5904
	ds_read_u16 v113, v183 offset:6048
	ds_read_u16 v114, v183 offset:6192
	s_waitcnt lgkmcnt(7)
	v_lshlrev_b32_e32 v52, 16, v52
	v_mul_f32_e32 v32, v32, v52
	v_cvt_pk_bf16_f32 v32, v32, s0
	ds_write_b16 v183, v32 offset:4608
	v_sub_f32_e32 v32, v33, v61
	v_mul_f32_e32 v33, v138, v109
	v_fmac_f32_e32 v33, v139, v32
	v_add_f32_e32 v32, v53, v33
	s_waitcnt lgkmcnt(7)
	v_lshlrev_b32_e32 v33, 16, v60
	v_mul_f32_e32 v32, v32, v33
	v_cvt_pk_bf16_f32 v32, v32, s0
	ds_write_b16 v183, v32 offset:4752
	v_sub_f32_e32 v32, v34, v62
	v_mul_f32_e32 v33, v138, v110
	v_fmac_f32_e32 v33, v139, v32
	v_add_f32_e32 v32, v54, v33
	s_waitcnt lgkmcnt(7)
	v_lshlrev_b32_e32 v33, 16, v104
	v_mul_f32_e32 v32, v32, v33
	v_cvt_pk_bf16_f32 v32, v32, s0
	ds_write_b16 v183, v32 offset:4896
	v_sub_f32_e32 v32, v35, v63
	v_mul_f32_e32 v33, v138, v111
	v_fmac_f32_e32 v33, v139, v32
	v_add_f32_e32 v32, v55, v33
	s_waitcnt lgkmcnt(7)
	v_lshlrev_b32_e32 v33, 16, v105
	v_mul_f32_e32 v32, v32, v33
	v_cvt_pk_bf16_f32 v32, v32, s0
	ds_write_b16 v183, v32 offset:5040
	v_lshl_add_u64 v[32:33], s[10:11], 0, v[162:163]
	v_lshl_add_u64 v[32:33], v[32:33], 2, s[28:29]
	ds_read_b128 v[52:55], v188 offset:1536
	ds_read_b128 v[60:63], v188 offset:1024
	global_load_dwordx4 v[104:107], v[32:33], off offset:128
	v_mfma_f32_32x32x16_bf16 v[16:31], v[92:95], v[96:99], v[16:31]
	s_waitcnt lgkmcnt(1)
	v_sub_f32_e32 v34, v36, v52
	s_waitcnt lgkmcnt(0)
	v_mul_f32_e32 v35, v138, v60
	v_fmac_f32_e32 v35, v139, v34
	s_waitcnt vmcnt(2)
	v_add_f32_e32 v34, v56, v35
	v_lshlrev_b32_e32 v35, 16, v108
	v_mul_f32_e32 v34, v34, v35
	v_cvt_pk_bf16_f32 v34, v34, s0
	ds_write_b16 v183, v34 offset:5760
	v_sub_f32_e32 v34, v37, v53
	v_mul_f32_e32 v35, v138, v61
	v_fmac_f32_e32 v35, v139, v34
	v_add_f32_e32 v34, v57, v35
	v_lshlrev_b32_e32 v35, 16, v112
	v_mul_f32_e32 v34, v34, v35
	v_cvt_pk_bf16_f32 v34, v34, s0
	ds_write_b16 v183, v34 offset:5904
	v_sub_f32_e32 v34, v38, v54
	v_mul_f32_e32 v35, v138, v62
	v_fmac_f32_e32 v35, v139, v34
	v_add_f32_e32 v34, v58, v35
	v_lshlrev_b32_e32 v35, 16, v113
	v_mul_f32_e32 v34, v34, v35
	v_cvt_pk_bf16_f32 v34, v34, s0
	ds_write_b16 v183, v34 offset:6048
	v_sub_f32_e32 v34, v39, v55
	v_mul_f32_e32 v35, v138, v63
	v_fmac_f32_e32 v35, v139, v34
	v_add_f32_e32 v38, v59, v35
	ds_read_b128 v[34:37], v189 offset:1536
	ds_read_b128 v[52:55], v189 offset:1024
	v_lshlrev_b32_e32 v39, 16, v114
	v_mul_f32_e32 v38, v38, v39
	v_cvt_pk_bf16_f32 v38, v38, s0
	ds_write_b16 v183, v38 offset:6192
	s_waitcnt lgkmcnt(2)
	v_sub_f32_e32 v34, v40, v34
	s_waitcnt lgkmcnt(1)
	v_mul_f32_e32 v38, v138, v52
	v_fmac_f32_e32 v38, v139, v34
	s_waitcnt vmcnt(1)
	v_add_f32_e32 v34, v100, v38
	ds_read_u16 v38, v183 offset:6912
	ds_read_u16 v39, v183 offset:7056
	ds_read_u16 v40, v183 offset:7200
	ds_read_u16 v52, v183 offset:7344
	ds_read_u16 v56, v183 offset:8064
	ds_read_u16 v57, v183 offset:8208
	ds_read_u16 v58, v183 offset:8352
	ds_read_u16 v59, v183 offset:8496
	s_waitcnt lgkmcnt(7)
	v_lshlrev_b32_e32 v38, 16, v38
	v_mul_f32_e32 v34, v34, v38
	v_cvt_pk_bf16_f32 v34, v34, s0
	ds_write_b16 v183, v34 offset:6912
	v_sub_f32_e32 v34, v41, v35
	v_mul_f32_e32 v35, v138, v53
	v_fmac_f32_e32 v35, v139, v34
	v_add_f32_e32 v34, v101, v35
	s_waitcnt lgkmcnt(7)
	v_lshlrev_b32_e32 v35, 16, v39
	v_mul_f32_e32 v34, v34, v35
	v_cvt_pk_bf16_f32 v34, v34, s0
	ds_write_b16 v183, v34 offset:7056
	v_sub_f32_e32 v34, v42, v36
	v_mul_f32_e32 v35, v138, v54
	v_fmac_f32_e32 v35, v139, v34
	v_add_f32_e32 v34, v102, v35
	s_waitcnt lgkmcnt(7)
	v_lshlrev_b32_e32 v35, 16, v40
	v_mul_f32_e32 v34, v34, v35
	v_cvt_pk_bf16_f32 v34, v34, s0
	ds_write_b16 v183, v34 offset:7200
	v_sub_f32_e32 v34, v43, v37
	v_mul_f32_e32 v35, v138, v55
	v_fmac_f32_e32 v35, v139, v34
	v_add_f32_e32 v42, v103, v35
	ds_read_b128 v[34:37], v190 offset:1536
	ds_read_b128 v[38:41], v190 offset:1024
	s_waitcnt lgkmcnt(9)
	v_lshlrev_b32_e32 v43, 16, v52
	v_mul_f32_e32 v42, v42, v43
	v_cvt_pk_bf16_f32 v42, v42, s0
	s_waitcnt lgkmcnt(1)
	v_sub_f32_e32 v34, v44, v34
	s_waitcnt lgkmcnt(0)
	v_mul_f32_e32 v38, v138, v38
	v_fmac_f32_e32 v38, v139, v34
	ds_write_b16 v183, v42 offset:7344
	v_mfma_f32_32x32x16_bf16 v[16:31], v[84:87], v[76:79], v[16:31]
	s_waitcnt vmcnt(0)
	v_add_f32_e32 v34, v104, v38
	v_lshlrev_b32_e32 v38, 16, v56
	v_mul_f32_e32 v34, v34, v38
	v_cvt_pk_bf16_f32 v34, v34, s0
	ds_write_b16 v183, v34 offset:8064
	v_sub_f32_e32 v34, v45, v35
	v_mul_f32_e32 v35, v138, v39
	v_fmac_f32_e32 v35, v139, v34
	v_add_f32_e32 v34, v105, v35
	v_lshlrev_b32_e32 v35, 16, v57
	v_mul_f32_e32 v34, v34, v35
	v_cvt_pk_bf16_f32 v34, v34, s0
	ds_write_b16 v183, v34 offset:8208
	v_sub_f32_e32 v34, v46, v36
	v_mul_f32_e32 v35, v138, v40
	v_fmac_f32_e32 v35, v139, v34
	v_add_f32_e32 v34, v106, v35
	v_lshlrev_b32_e32 v35, 16, v58
	v_mul_f32_e32 v34, v34, v35
	v_cvt_pk_bf16_f32 v34, v34, s0
	ds_write_b16 v183, v34 offset:8352
	v_sub_f32_e32 v34, v47, v37
	v_mul_f32_e32 v35, v138, v41
	v_fmac_f32_e32 v35, v139, v34
	v_add_f32_e32 v34, v107, v35
	v_lshlrev_b32_e32 v35, 16, v59
	v_mul_f32_e32 v34, v34, v35
	v_cvt_pk_bf16_f32 v34, v34, s0
	ds_write_b16 v183, v34 offset:8496
	global_load_dword v34, v[170:171], off offset:128
	global_load_dword v35, v[136:137], off offset:128
	global_load_dword v56, v[134:135], off
	global_load_dwordx3 v[60:62], v[132:133], off offset:4
	global_load_dwordx4 v[36:39], v[132:133], off offset:32
	v_mfma_f32_32x32x16_bf16 v[16:31], v[80:83], v[68:71], v[16:31]
	ds_read_b128 v[40:43], v182 offset:1536
	ds_read_b128 v[44:47], v182 offset:1024
	global_load_dwordx4 v[52:55], v[132:133], off offset:64
	v_mfma_f32_32x32x16_bf16 v[0:15], v[88:91], v[96:99], v[0:15]
	s_waitcnt lgkmcnt(1)
	s_nop 6
	v_sub_f32_e32 v16, v16, v40
	s_waitcnt vmcnt(5) lgkmcnt(0)
	v_mul_f32_e32 v40, v34, v44
	ds_read_u16 v44, v183 offset:64
	s_waitcnt vmcnt(4)
	v_fmac_f32_e32 v40, v35, v16
	s_waitcnt vmcnt(3)
	v_add_f32_e32 v16, v56, v40
	ds_read_b128 v[56:59], v184 offset:1024
	v_mfma_f32_32x32x16_bf16 v[0:15], v[72:75], v[76:79], v[0:15]
	s_waitcnt lgkmcnt(1)
	v_lshlrev_b32_e32 v40, 16, v44
	v_mul_f32_e32 v16, v16, v40
	v_cvt_pk_bf16_f32 v16, v16, s0
	ds_write_b16 v183, v16 offset:64
	v_sub_f32_e32 v16, v17, v41
	v_mul_f32_e32 v16, v35, v16
	v_fmac_f32_e32 v16, v34, v45
	s_waitcnt vmcnt(2)
	v_add_f32_e32 v16, v60, v16
	ds_read_u16 v17, v193 offset:64
	ds_read_u16 v40, v193 offset:208
	ds_read_u16 v41, v193 offset:352
	ds_read_u16 v60, v193 offset:1072
	ds_read_u16 v63, v193 offset:1216
	ds_read_u16 v80, v193 offset:1360
	ds_read_u16 v81, v193 offset:1504
	ds_read_u16 v82, v193 offset:2224
	s_waitcnt lgkmcnt(7)
	v_lshlrev_b32_e32 v17, 16, v17
	v_mul_f32_e32 v16, v16, v17
	v_cvt_pk_bf16_f32 v16, v16, s0
	ds_write_b16 v193, v16 offset:64
	v_sub_f32_e32 v16, v18, v42
	v_mul_f32_e32 v16, v35, v16
	v_fmac_f32_e32 v16, v34, v46
	v_add_f32_e32 v16, v61, v16
	s_waitcnt lgkmcnt(7)
	v_lshlrev_b32_e32 v17, 16, v40
	v_mul_f32_e32 v16, v16, v17
	v_cvt_pk_bf16_f32 v16, v16, s0
	ds_write_b16 v193, v16 offset:208
	v_sub_f32_e32 v16, v19, v43
	v_mul_f32_e32 v16, v35, v16
	v_fmac_f32_e32 v16, v34, v47
	v_add_f32_e32 v16, v62, v16
	s_waitcnt lgkmcnt(7)
	v_lshlrev_b32_e32 v17, 16, v41
	v_mul_f32_e32 v40, v16, v17
	v_cvt_pk_bf16_f32 v44, v40, s0
	global_load_dwordx4 v[40:43], v[132:133], off offset:96
	ds_read_b128 v[16:19], v184 offset:1536
	ds_write_b16 v193, v44 offset:352
	ds_read_b128 v[44:47], v185 offset:1024
	v_mfma_f32_32x32x16_bf16 v[0:15], v[64:67], v[68:71], v[0:15]
	s_waitcnt lgkmcnt(2)
	v_sub_f32_e32 v16, v20, v16
	v_mul_f32_e32 v16, v35, v16
	v_fmac_f32_e32 v16, v34, v56
	s_waitcnt vmcnt(2)
	v_add_f32_e32 v16, v36, v16
	v_lshlrev_b32_e32 v20, 16, v60
	v_mul_f32_e32 v16, v16, v20
	v_cvt_pk_bf16_f32 v16, v16, s0
	ds_write_b16 v193, v16 offset:1072
	v_sub_f32_e32 v16, v21, v17
	v_mul_f32_e32 v16, v35, v16
	v_fmac_f32_e32 v16, v34, v57
	v_add_f32_e32 v16, v37, v16
	v_lshlrev_b32_e32 v17, 16, v63
	v_mul_f32_e32 v16, v16, v17
	v_cvt_pk_bf16_f32 v16, v16, s0
	ds_write_b16 v193, v16 offset:1216
	v_sub_f32_e32 v16, v22, v18
	v_mul_f32_e32 v16, v35, v16
	v_fmac_f32_e32 v16, v34, v58
	v_add_f32_e32 v16, v38, v16
	v_lshlrev_b32_e32 v17, 16, v80
	v_mul_f32_e32 v16, v16, v17
	v_cvt_pk_bf16_f32 v16, v16, s0
	ds_write_b16 v193, v16 offset:1360
	v_sub_f32_e32 v16, v23, v19
	v_mul_f32_e32 v16, v35, v16
	v_fmac_f32_e32 v16, v34, v59
	v_add_f32_e32 v20, v39, v16
	ds_read_b128 v[16:19], v185 offset:1536
	v_lshlrev_b32_e32 v21, 16, v81
	v_mul_f32_e32 v20, v20, v21
	v_cvt_pk_bf16_f32 v20, v20, s0
	ds_write_b16 v193, v20 offset:1504
	s_waitcnt lgkmcnt(1)
	v_sub_f32_e32 v16, v24, v16
	v_mul_f32_e32 v16, v35, v16
	v_fmac_f32_e32 v16, v34, v44
	s_waitcnt vmcnt(1)
	v_add_f32_e32 v16, v52, v16
	v_lshlrev_b32_e32 v24, 16, v82
	v_mul_f32_e32 v16, v16, v24
	v_cvt_pk_bf16_f32 v16, v16, s0
	ds_write_b16 v193, v16 offset:2224
	v_sub_f32_e32 v16, v25, v17
	v_mul_f32_e32 v16, v35, v16
	ds_read_b128 v[20:23], v186 offset:1024
	v_fmac_f32_e32 v16, v34, v45
	ds_read_u16 v17, v193 offset:2368
	ds_read_u16 v24, v193 offset:2512
	ds_read_u16 v25, v193 offset:2656
	ds_read_u16 v36, v193 offset:3376
	ds_read_u16 v37, v193 offset:3520
	ds_read_u16 v38, v193 offset:3664
	ds_read_u16 v39, v193 offset:3808
	v_add_f32_e32 v16, v53, v16
	s_waitcnt lgkmcnt(6)
	v_lshlrev_b32_e32 v17, 16, v17
	v_mul_f32_e32 v16, v16, v17
	v_cvt_pk_bf16_f32 v16, v16, s0
	ds_write_b16 v193, v16 offset:2368
	v_sub_f32_e32 v16, v26, v18
	v_mul_f32_e32 v16, v35, v16
	v_fmac_f32_e32 v16, v34, v46
	v_add_f32_e32 v16, v54, v16
	s_waitcnt lgkmcnt(6)
	v_lshlrev_b32_e32 v17, 16, v24
	v_mul_f32_e32 v16, v16, v17
	v_cvt_pk_bf16_f32 v16, v16, s0
	ds_write_b16 v193, v16 offset:2512
	v_sub_f32_e32 v16, v27, v19
	v_mul_f32_e32 v16, v35, v16
	v_fmac_f32_e32 v16, v34, v47
	v_add_f32_e32 v24, v55, v16
	ds_read_b128 v[16:19], v186 offset:1536
	s_waitcnt lgkmcnt(7)
	v_lshlrev_b32_e32 v25, 16, v25
	v_mul_f32_e32 v24, v24, v25
	v_cvt_pk_bf16_f32 v24, v24, s0
	ds_write_b16 v193, v24 offset:2656
	s_waitcnt lgkmcnt(1)
	v_sub_f32_e32 v16, v28, v16
	v_mul_f32_e32 v16, v35, v16
	v_fmac_f32_e32 v16, v34, v20
	v_lshlrev_b32_e32 v20, 16, v36
	s_waitcnt vmcnt(0)
	v_add_f32_e32 v16, v40, v16
	v_mul_f32_e32 v16, v16, v20
	v_cvt_pk_bf16_f32 v16, v16, s0
	ds_write_b16 v193, v16 offset:3376
	v_sub_f32_e32 v16, v29, v17
	v_mul_f32_e32 v16, v35, v16
	v_fmac_f32_e32 v16, v34, v21
	v_add_f32_e32 v16, v41, v16
	v_lshlrev_b32_e32 v17, 16, v37
	v_mul_f32_e32 v16, v16, v17
	v_cvt_pk_bf16_f32 v16, v16, s0
	ds_write_b16 v193, v16 offset:3520
	v_sub_f32_e32 v16, v30, v18
	v_mul_f32_e32 v16, v35, v16
	v_fmac_f32_e32 v16, v34, v22
	v_add_f32_e32 v16, v42, v16
	v_lshlrev_b32_e32 v17, 16, v38
	v_mul_f32_e32 v16, v16, v17
	v_cvt_pk_bf16_f32 v16, v16, s0
	ds_write_b16 v193, v16 offset:3664
	v_sub_f32_e32 v16, v31, v19
	v_mul_f32_e32 v16, v35, v16
	v_fmac_f32_e32 v16, v34, v23
	v_add_f32_e32 v16, v43, v16
	v_lshlrev_b32_e32 v17, 16, v39
	v_mul_f32_e32 v16, v16, v17
	v_cvt_pk_bf16_f32 v16, v16, s0
	ds_write_b16 v193, v16 offset:3808
	global_load_dwordx4 v[16:19], v[132:133], off offset:128
	global_load_dwordx4 v[20:23], v[48:49], off offset:128
	ds_read_b128 v[24:27], v187 offset:1536
	ds_read_b128 v[28:31], v187 offset:1024
	global_load_dwordx4 v[36:39], v[50:51], off offset:128
	s_waitcnt lgkmcnt(1)
	v_sub_f32_e32 v0, v0, v24
	s_waitcnt lgkmcnt(0)
	v_mul_f32_e32 v24, v34, v28
	v_fmac_f32_e32 v24, v35, v0
	s_waitcnt vmcnt(2)
	v_add_f32_e32 v0, v16, v24
	ds_read_u16 v16, v183 offset:4672
	ds_read_u16 v24, v183 offset:4816
	ds_read_u16 v28, v183 offset:4960
	ds_read_u16 v40, v183 offset:5104
	ds_read_u16 v41, v183 offset:5824
	ds_read_u16 v42, v183 offset:5968
	ds_read_u16 v43, v183 offset:6112
	ds_read_u16 v44, v183 offset:6256
	s_waitcnt lgkmcnt(7)
	v_lshlrev_b32_e32 v16, 16, v16
	v_mul_f32_e32 v0, v0, v16
	v_cvt_pk_bf16_f32 v0, v0, s0
	ds_write_b16 v183, v0 offset:4672
	v_sub_f32_e32 v0, v1, v25
	v_mul_f32_e32 v0, v35, v0
	v_fmac_f32_e32 v0, v34, v29
	v_add_f32_e32 v0, v17, v0
	s_waitcnt lgkmcnt(7)
	v_lshlrev_b32_e32 v1, 16, v24
	v_mul_f32_e32 v0, v0, v1
	v_cvt_pk_bf16_f32 v0, v0, s0
	ds_write_b16 v183, v0 offset:4816
	v_sub_f32_e32 v0, v2, v26
	v_mul_f32_e32 v0, v35, v0
	v_fmac_f32_e32 v0, v34, v30
	v_add_f32_e32 v0, v18, v0
	s_waitcnt lgkmcnt(7)
	v_lshlrev_b32_e32 v1, 16, v28
	v_mul_f32_e32 v0, v0, v1
	v_cvt_pk_bf16_f32 v0, v0, s0
	ds_write_b16 v183, v0 offset:4960
	v_sub_f32_e32 v0, v3, v27
	v_mul_f32_e32 v0, v35, v0
	v_fmac_f32_e32 v0, v34, v31
	v_add_f32_e32 v24, v19, v0
	s_waitcnt lgkmcnt(7)
	v_lshlrev_b32_e32 v25, 16, v40
	v_mul_f32_e32 v24, v24, v25
	v_cvt_pk_bf16_f32 v24, v24, s0
	ds_read_b128 v[0:3], v188 offset:1024
	ds_read_b128 v[16:19], v188 offset:1536
	ds_write_b16 v183, v24 offset:5104
	global_load_dwordx4 v[24:27], v[32:33], off offset:128
	s_waitcnt lgkmcnt(1)
	v_sub_f32_e32 v4, v4, v16
	v_mul_f32_e32 v4, v35, v4
	v_fmac_f32_e32 v4, v34, v0
	s_waitcnt vmcnt(2)
	v_add_f32_e32 v0, v20, v4
	v_lshlrev_b32_e32 v4, 16, v41
	v_mul_f32_e32 v0, v0, v4
	v_cvt_pk_bf16_f32 v0, v0, s0
	ds_write_b16 v183, v0 offset:5824
	v_sub_f32_e32 v0, v5, v17
	v_mul_f32_e32 v0, v35, v0
	v_fmac_f32_e32 v0, v34, v1
	v_add_f32_e32 v0, v21, v0
	v_lshlrev_b32_e32 v1, 16, v42
	v_mul_f32_e32 v0, v0, v1
	v_cvt_pk_bf16_f32 v0, v0, s0
	ds_write_b16 v183, v0 offset:5968
	v_sub_f32_e32 v0, v6, v18
	v_mul_f32_e32 v0, v35, v0
	v_fmac_f32_e32 v0, v34, v2
	v_add_f32_e32 v0, v22, v0
	v_lshlrev_b32_e32 v1, 16, v43
	v_mul_f32_e32 v0, v0, v1
	v_cvt_pk_bf16_f32 v0, v0, s0
	ds_write_b16 v183, v0 offset:6112
	v_sub_f32_e32 v0, v7, v19
	v_mul_f32_e32 v0, v35, v0
	v_fmac_f32_e32 v0, v34, v3
	v_add_f32_e32 v16, v23, v0
	ds_read_b128 v[0:3], v189 offset:1024
	ds_read_b128 v[4:7], v189 offset:1536
	v_lshlrev_b32_e32 v17, 16, v44
	v_mul_f32_e32 v16, v16, v17
	v_cvt_pk_bf16_f32 v16, v16, s0
	ds_write_b16 v183, v16 offset:6256
	s_waitcnt lgkmcnt(1)
	v_sub_f32_e32 v4, v8, v4
	v_mul_f32_e32 v4, v35, v4
	v_fmac_f32_e32 v4, v34, v0
	s_waitcnt vmcnt(1)
	v_add_f32_e32 v0, v36, v4
	ds_read_u16 v4, v183 offset:6976
	ds_read_u16 v8, v183 offset:7120
	ds_read_u16 v16, v183 offset:7264
	ds_read_u16 v17, v183 offset:7408
	ds_read_u16 v18, v183 offset:8128
	ds_read_u16 v19, v183 offset:8272
	ds_read_u16 v20, v183 offset:8416
	ds_read_u16 v21, v183 offset:8560
	s_waitcnt lgkmcnt(7)
	v_lshlrev_b32_e32 v4, 16, v4
	v_mul_f32_e32 v0, v0, v4
	v_cvt_pk_bf16_f32 v0, v0, s0
	ds_write_b16 v183, v0 offset:6976
	v_sub_f32_e32 v0, v9, v5
	v_mul_f32_e32 v0, v35, v0
	v_fmac_f32_e32 v0, v34, v1
	v_add_f32_e32 v0, v37, v0
	s_waitcnt lgkmcnt(7)
	v_lshlrev_b32_e32 v1, 16, v8
	v_mul_f32_e32 v0, v0, v1
	v_cvt_pk_bf16_f32 v0, v0, s0
	ds_write_b16 v183, v0 offset:7120
	v_sub_f32_e32 v0, v10, v6
	v_mul_f32_e32 v0, v35, v0
	v_fmac_f32_e32 v0, v34, v2
	v_add_f32_e32 v0, v38, v0
	s_waitcnt lgkmcnt(7)
	v_lshlrev_b32_e32 v1, 16, v16
	v_mul_f32_e32 v0, v0, v1
	v_cvt_pk_bf16_f32 v0, v0, s0
	ds_write_b16 v183, v0 offset:7264
	v_sub_f32_e32 v0, v11, v7
	v_mul_f32_e32 v0, v35, v0
	v_fmac_f32_e32 v0, v34, v3
	v_add_f32_e32 v8, v39, v0
	ds_read_b128 v[0:3], v190 offset:1024
	ds_read_b128 v[4:7], v190 offset:1536
	s_waitcnt lgkmcnt(9)
	v_lshlrev_b32_e32 v9, 16, v17
	v_mul_f32_e32 v8, v8, v9
	v_cvt_pk_bf16_f32 v8, v8, s0
	ds_write_b16 v183, v8 offset:7408
	s_waitcnt lgkmcnt(1)
	v_sub_f32_e32 v4, v12, v4
	v_mul_f32_e32 v4, v35, v4
	v_fmac_f32_e32 v4, v34, v0
	s_waitcnt vmcnt(0)
	v_add_f32_e32 v0, v24, v4
	v_lshlrev_b32_e32 v4, 16, v18
	v_mul_f32_e32 v0, v0, v4
	v_cvt_pk_bf16_f32 v0, v0, s0
	ds_write_b16 v183, v0 offset:8128
	v_sub_f32_e32 v0, v13, v5
	v_mul_f32_e32 v0, v35, v0
	v_fmac_f32_e32 v0, v34, v1
	v_add_f32_e32 v0, v25, v0
	v_lshlrev_b32_e32 v1, 16, v19
	v_mul_f32_e32 v0, v0, v1
	v_cvt_pk_bf16_f32 v0, v0, s0
	ds_write_b16 v183, v0 offset:8272
	v_sub_f32_e32 v0, v14, v6
	v_mul_f32_e32 v0, v35, v0
	v_fmac_f32_e32 v0, v34, v2
	v_add_f32_e32 v0, v26, v0
	v_lshlrev_b32_e32 v1, 16, v20
	v_mul_f32_e32 v0, v0, v1
	v_cvt_pk_bf16_f32 v0, v0, s0
	ds_write_b16 v183, v0 offset:8416
	v_sub_f32_e32 v0, v15, v7
	v_mul_f32_e32 v0, v35, v0
	v_fmac_f32_e32 v0, v34, v3
	v_add_f32_e32 v0, v27, v0
	v_lshlrev_b32_e32 v1, 16, v21
	v_mul_f32_e32 v0, v0, v1
	v_cvt_pk_bf16_f32 v0, v0, s0
	ds_write_b16 v183, v0 offset:8560
	s_waitcnt lgkmcnt(0)
	v_mov_b32_e32 v0, v192
